# P1: gate bias + log-sigmoid + stores batched once per 4 rows on 32 lanes instead of per row on 8 lanes
# speedup vs baseline: 1.0018x; 1.0000x over previous
; DI void phase1(const Params& p, unsigned char* smem) {
;     ...
;     const float* mod = (const float*)(ws + OFF_MOD);
;     bf16_t* h1 = (bf16_t*)(ws + 1 * U_);
;     float4 gw0[16], gw1[16];
; #pragma unroll
;     for (int i = 0; i < 4; ++i)
; #pragma unroll
;         for (int e = 0; e < 4; ++e) {
;             const float* wp = p.in[4] + (size_t)(i * 256 + lane * 4 + e) * 4616 + 2048;
;             gw0[i * 4 + e] = *(const float4*)wp; gw1[i * 4 + e] = *(const float4*)(wp + 4);
;         }
;     float* ig = (float*)(ws + OFF_IG);
;     float* lf = (float*)(ws + OFF_LOGF);
;     for (int row0 = (blockIdx.x * 8 + wid) * 4; row0 < T_; row0 += gridDim.x * 32) {
.LBB0_184:
	s_or_b64 exec, exec, s[0:1]
	s_add_u32 s62, s70, 0x2000000
	s_addc_u32 s63, s71, 0
	s_add_u32 s94, s70, 0x4000000
	s_addc_u32 s95, s71, 0
	s_add_u32 s88, s70, 0x325c000
	v_mov_b32_e32 v0, v250
	s_addc_u32 s89, s71, 0
	s_waitcnt lgkmcnt(0)
	s_barrier
	v_lshlrev_b32_e32 v150, 4, v250
	v_add_u32_e32 v151, 0x6000, v150
	v_add_u32_e32 v152, 0xc000, v150
	v_add_u32_e32 v153, 0x12000, v150
	global_load_dwordx4 v[156:159], v150, s[62:63]
	global_load_dwordx4 v[160:163], v151, s[62:63]
	global_load_dwordx4 v[164:167], v152, s[62:63]
	global_load_dwordx4 v[168:171], v153, s[62:63]
	s_waitcnt vmcnt(3)
	ds_write_b128 v150, v[156:159] offset:1024
	s_waitcnt vmcnt(2)
	ds_write_b128 v150, v[160:163] offset:9216
	s_waitcnt vmcnt(1)
	ds_write_b128 v150, v[164:167] offset:17408
	s_waitcnt vmcnt(0)
	ds_write_b128 v150, v[168:171] offset:25600
	s_waitcnt lgkmcnt(0)
	s_barrier
	s_add_u32 s20, s70, 0x32dc000
	v_ashrrev_i32_e32 v1, 4, v0
	s_addc_u32 s21, s71, 0
	s_lshl_b32 s0, s2, 5
	v_and_b32_e32 v1, -4, v1
	v_writelane_b32 v254, s0, 52
	v_add_u32_e32 v176, s0, v1
	s_mov_b32 s0, 0x8000
	v_cmp_gt_i32_e32 vcc, s0, v176
	s_and_saveexec_b64 s[22:23], vcc
	s_cbranch_execz .LBB0_219
	v_and_b32_e32 v230, 63, v0
	v_mul_u32_u24_e32 v0, 0x4820, v230
	v_readlane_b32 s36, v254, 4
	v_lshlrev_b32_e32 v178, 2, v0
	v_mov_b32_e32 v179, 0
	v_readlane_b32 s44, v254, 12
	v_readlane_b32 s45, v254, 13
	v_lshlrev_b32_e32 v128, 2, v230
	v_or_b32_e32 v130, 0x100, v128
	v_lshl_add_u64 v[16:17], s[44:45], 0, v[178:179]
	v_add_co_u32_e32 v0, vcc, 0x2000, v16
	s_mov_b64 s[0:1], 0x6820
	s_nop 0
	v_addc_co_u32_e32 v1, vcc, 0, v17, vcc
	v_add_co_u32_e32 v8, vcc, 0x6000, v16
	v_mul_u32_u24_e32 v22, 0x1208, v130
	s_nop 0
	v_addc_co_u32_e32 v9, vcc, 0, v17, vcc
	v_add_co_u32_e32 v18, vcc, 0xb000, v16
	v_lshl_add_u64 v[12:13], v[16:17], 0, s[0:1]
	s_nop 0
	v_addc_co_u32_e32 v19, vcc, 0, v17, vcc
	s_mov_b64 s[0:1], 0xb040
	v_add_co_u32_e32 v24, vcc, 0xf000, v16
	v_lshlrev_b32_e32 v178, 2, v22
	s_movk_i32 s3, 0x2000
	v_lshl_add_u64 v[20:21], v[16:17], 0, s[0:1]
	s_mov_b64 s[0:1], 0xf860
	v_addc_co_u32_e32 v25, vcc, 0, v17, vcc
	v_lshl_add_u64 v[22:23], s[44:45], 0, v[178:179]
	v_lshl_add_u64 v[28:29], v[16:17], 0, s[0:1]
	v_add_co_u32_e32 v32, vcc, s3, v22
	s_mov_b64 s[0:1], 0x488820
	s_nop 0
	v_addc_co_u32_e32 v33, vcc, 0, v23, vcc
	v_lshl_add_u64 v[44:45], v[16:17], 0, s[0:1]
	s_mov_b32 s0, 0x488000
	v_add_co_u32_e32 v40, vcc, s0, v16
	s_mov_b64 s[0:1], 0x48d040
	s_nop 0
	v_addc_co_u32_e32 v41, vcc, 0, v17, vcc
	v_lshl_add_u64 v[52:53], v[16:17], 0, s[0:1]
	s_mov_b32 s0, 0x48d000
	v_add_co_u32_e32 v48, vcc, s0, v16
	s_mov_b64 s[0:1], 0x491860
	s_nop 0
	v_addc_co_u32_e32 v49, vcc, 0, v17, vcc
	v_lshl_add_u64 v[60:61], v[16:17], 0, s[0:1]
	s_mov_b32 s0, 0x491000
	v_add_co_u32_e32 v56, vcc, s0, v16
	s_mov_b64 s[0:1], 0x484000
	s_nop 0
	v_addc_co_u32_e32 v57, vcc, 0, v17, vcc
	v_lshl_add_u64 v[68:69], v[22:23], 0, s[0:1]
	s_mov_b32 s0, 0x484000
	v_add_co_u32_e32 v64, vcc, s0, v22
	s_mov_b64 s[0:1], 0x90a820
	s_nop 0
	v_addc_co_u32_e32 v65, vcc, 0, v23, vcc
	v_lshl_add_u64 v[76:77], v[16:17], 0, s[0:1]
	s_mov_b32 s0, 0x90a000
	v_add_co_u32_e32 v72, vcc, s0, v16
	s_mov_b64 s[0:1], 0x90f040
	s_nop 0
	v_addc_co_u32_e32 v73, vcc, 0, v17, vcc
	v_lshl_add_u64 v[84:85], v[16:17], 0, s[0:1]
	s_mov_b32 s0, 0x90f000
	v_add_co_u32_e32 v80, vcc, s0, v16
	s_mov_b64 s[0:1], 0x913860
	s_nop 0
	v_addc_co_u32_e32 v81, vcc, 0, v17, vcc
	v_lshl_add_u64 v[92:93], v[16:17], 0, s[0:1]
	s_mov_b32 s0, 0x913000
	v_add_co_u32_e32 v88, vcc, s0, v16
	s_mov_b64 s[0:1], 0x906000
	s_nop 0
	v_addc_co_u32_e32 v89, vcc, 0, v17, vcc
	v_lshl_add_u64 v[100:101], v[22:23], 0, s[0:1]
	s_mov_b32 s0, 0x906000
	v_add_co_u32_e32 v96, vcc, s0, v22
	s_mov_b64 s[0:1], 0xd8c820
	s_nop 0
	v_addc_co_u32_e32 v97, vcc, 0, v23, vcc
	v_lshl_add_u64 v[108:109], v[16:17], 0, s[0:1]
	s_mov_b32 s0, 0xd8c000
	v_add_co_u32_e32 v104, vcc, s0, v16
	s_mov_b64 s[0:1], 0xd91040
	s_nop 0
	v_addc_co_u32_e32 v105, vcc, 0, v17, vcc
	v_lshl_add_u64 v[116:117], v[16:17], 0, s[0:1]
	s_mov_b32 s0, 0xd91000
	v_add_co_u32_e32 v112, vcc, s0, v16
	s_mov_b64 s[0:1], 0xd95860
	s_nop 0
	v_addc_co_u32_e32 v113, vcc, 0, v17, vcc
	v_lshl_add_u64 v[124:125], v[16:17], 0, s[0:1]
	s_mov_b32 s0, 0xd95000
	s_mov_b64 s[16:17], 0x2000
	v_add_co_u32_e32 v120, vcc, s0, v16
; DI void phase1(const Params& p, unsigned char* smem) {
;     ...
;     float4 gw0[16], gw1[16];
; #pragma unroll
;     for (int i = 0; i < 4; ++i)
; #pragma unroll
;         for (int e = 0; e < 4; ++e) {
;             const float* wp = p.in[4] + (size_t)(i * 256 + lane * 4 + e) * 4616 + 2048;
;             gw0[i * 4 + e] = *(const float4*)wp; gw1[i * 4 + e] = *(const float4*)(wp + 4);
;         }
;     float* ig = (float*)(ws + OFF_IG);
;     float* lf = (float*)(ws + OFF_LOGF);
;     for (int row0 = (blockIdx.x * 8 + wid) * 4; row0 < T_; row0 += gridDim.x * 32) {
;     ...
;             if (lane < 8) {
;                 float val = ga[0];
; #pragma unroll
;                 for (int j = 1; j < 8; ++j) val = (lane == j) ? ga[j] : val;
;                 val += p.in[5][2048 + lane];
;                 const int b = row >> 13, sidx = row & 8191;
;                 if (lane < 4) ig[(size_t)(b * 4 + lane) * 8192 + sidx] = val;
	v_lshl_add_u64 v[4:5], v[16:17], 0, s[16:17]
	v_lshl_add_u64 v[36:37], v[22:23], 0, s[16:17]
	v_addc_co_u32_e32 v121, vcc, 0, v17, vcc
	global_load_dwordx4 v[0:3], v[0:1], off
	s_nop 0
	global_load_dwordx4 v[4:7], v[4:5], off offset:16
	s_nop 0
	global_load_dwordx4 v[8:11], v[8:9], off offset:2080
	s_nop 0
	global_load_dwordx4 v[12:15], v[12:13], off offset:16
	s_nop 0
	global_load_dwordx4 v[16:19], v[18:19], off offset:64
	s_nop 0
	global_load_dwordx4 v[20:23], v[20:21], off offset:16
	s_nop 0
	global_load_dwordx4 v[24:27], v[24:25], off offset:2144
	s_nop 0
	global_load_dwordx4 v[28:31], v[28:29], off offset:16
	s_nop 0
	global_load_dwordx4 v[32:35], v[32:33], off
	s_nop 0
	global_load_dwordx4 v[36:39], v[36:37], off offset:16
	s_nop 0
	global_load_dwordx4 v[40:43], v[40:41], off offset:2080
	s_nop 0
	global_load_dwordx4 v[44:47], v[44:45], off offset:16
	s_nop 0
	global_load_dwordx4 v[48:51], v[48:49], off offset:64
	s_nop 0
	global_load_dwordx4 v[52:55], v[52:53], off offset:16
	s_nop 0
	global_load_dwordx4 v[56:59], v[56:57], off offset:2144
	s_nop 0
	global_load_dwordx4 v[60:63], v[60:61], off offset:16
	s_nop 0
	global_load_dwordx4 v[64:67], v[64:65], off
	s_nop 0
	global_load_dwordx4 v[68:71], v[68:69], off offset:16
	s_nop 0
	global_load_dwordx4 v[72:75], v[72:73], off offset:2080
	s_nop 0
	global_load_dwordx4 v[76:79], v[76:77], off offset:16
	s_nop 0
	global_load_dwordx4 v[80:83], v[80:81], off offset:64
	s_nop 0
	global_load_dwordx4 v[84:87], v[84:85], off offset:16
	s_nop 0
	global_load_dwordx4 v[88:91], v[88:89], off offset:2144
	s_nop 0
	global_load_dwordx4 v[92:95], v[92:93], off offset:16
	s_nop 0
	global_load_dwordx4 v[96:99], v[96:97], off
	s_nop 0
	global_load_dwordx4 v[100:103], v[100:101], off offset:16
	s_nop 0
	global_load_dwordx4 v[104:107], v[104:105], off offset:2080
	s_nop 0
	global_load_dwordx4 v[108:111], v[108:109], off offset:16
	s_nop 0
	global_load_dwordx4 v[112:115], v[112:113], off offset:64
	s_nop 0
	global_load_dwordx4 v[116:119], v[116:117], off offset:16
	s_nop 0
	global_load_dwordx4 v[120:123], v[120:121], off offset:2144
	s_nop 0
	global_load_dwordx4 v[124:127], v[124:125], off offset:16
	v_readlane_b32 s37, v254, 5
	v_readlane_b32 s46, v254, 14
	v_readlane_b32 s47, v254, 15
	v_mov_b32_e32 v129, v179
	v_lshlrev_b32_e32 v178, 4, v230
	v_readlane_b32 s38, v254, 6
	v_readlane_b32 s39, v254, 7
	v_readlane_b32 s40, v254, 8
	v_or_b32_e32 v132, 0x200, v128
	v_or_b32_e32 v134, 0x300, v128
	v_subrev_co_u32_e64 v231, s[0:1], 4, v230
	v_lshl_add_u64 v[180:181], s[36:37], 0, v[178:179]
	v_lshl_add_u64 v[136:137], s[46:47], 0, v[128:129]
	v_lshlrev_b32_e32 v178, 3, v230
	v_cmp_gt_u32_e32 vcc, 8, v230
	s_xor_b64 s[24:25], s[0:1], -1
	s_lshl_b32 s3, s33, 5
	v_cmp_eq_u32_e64 s[0:1], 1, v230
	v_cmp_eq_u32_e64 s[14:15], 2, v230
	v_cmp_eq_u32_e64 s[4:5], 3, v230
	v_cmp_eq_u32_e64 s[6:7], 4, v230
	v_cmp_eq_u32_e64 s[8:9], 5, v230
	v_cmp_eq_u32_e64 s[10:11], 6, v230
	v_cmp_eq_u32_e64 s[12:13], 7, v230
	v_lshl_add_u64 v[182:183], v[136:137], 0, s[16:17]
	v_lshl_add_u64 v[184:185], s[94:95], 0, v[178:179]
	s_mov_b64 s[26:27], 0
	v_lshlrev_b32_e32 v178, 2, v128
	v_lshlrev_b32_e32 v186, 2, v130
	v_lshlrev_b32_e32 v188, 2, v132
	v_lshlrev_b32_e32 v190, 2, v134
	v_mov_b32_e32 v232, 0x3727c5ac
	s_mov_b32 s36, 0x800000
	s_mov_b32 s37, 0x3f2aaaab
	v_mov_b32_e32 v233, 0x3ecc95a3
	s_mov_b32 s38, 0x3f317218
	s_mov_b32 s39, 0x7f800000
	s_mov_b32 s40, 0x33800000
	v_mov_b32_e32 v234, 0x7f800000
	v_mov_b32_e32 v235, 0x7fc00000
	v_mov_b32_e32 v236, 0xff800000
	v_mov_b32_e32 v192, 0x3f317218
	v_readlane_b32 s41, v254, 9
	v_readlane_b32 s42, v254, 10
	v_readlane_b32 s43, v254, 11
	v_readlane_b32 s48, v254, 16
	v_readlane_b32 s49, v254, 17
	v_readlane_b32 s50, v254, 18
	v_readlane_b32 s51, v254, 19
	v_and_b32_e32 v253, 0xfffffff8, v230
	v_cmp_gt_u32_e64 s[96:97], 32, v230
	v_lshlrev_b32_e32 v253, 2, v253
	v_and_b32_e32 v252, 4, v230
	v_cmp_ne_u32_e64 s[98:99], 0, v252
	v_sub_co_u32_e64 v252, s[100:101], v182, v253
	s_nop 1
	v_subbrev_co_u32_e64 v253, s[100:101], 0, v183, s[100:101]
	s_nop 0
	global_load_dword v252, v[252:253], off
	s_nop 0
	v_and_b32_e32 v253, 0x1c0, v250
	v_lshlrev_b32_e32 v253, 1, v253
	v_lshl_add_u32 v253, v230, 2, v253
	v_add_u32_e32 v253, 0xa000, v253
	global_load_dword v251, v[182:183], off
	s_branch .LBB0_189

; DI void row_stats(const float (&v)[16], float& mean, float& rstd) {
;     float s = 0.f;
; #pragma unroll
;     for (int i = 0; i < 16; ++i) s += v[i];
;     mean = wsum(s) * (1.f / 1024.f);
;     float q = 0.f;
; #pragma unroll
;     for (int i = 0; i < 16; ++i) { float d = v[i] - mean; q += d * d; }
;     rstd = rsqrtf(wsum(q) * (1.f / 1024.f) + 1e-5f);
; }
; DI void phase1(const Params& p, unsigned char* smem) {
;     ...
;         for (int rr = 0; rr < 4; ++rr)
; #pragma unroll
;             for (int i = 0; i < 4; ++i) { float4 t = *(const float4*)(p.in[0] + (size_t)(row0 + rr) * 1024 + i * 256 + lane * 4); vv[rr][4 * i] = t.x; vv[rr][4 * i + 1] = t.y; vv[rr][4 * i + 2] = t.z; vv[rr][4 * i + 3] = t.w; }
; #pragma unroll
;         for (int rr = 0; rr < 4; ++rr) {
;             const int row = row0 + rr;
;             float mean, rstd; row_stats(vv[rr], mean, rstd);
;             const float* mb = mod + (row >> 13) * 6144;
;             float ga[8];
; #pragma unroll
;             for (int j = 0; j < 8; ++j) ga[j] = 0.f;
; #pragma unroll
;             for (int i = 0; i < 4; ++i) {
;                 int c = i * 256 + lane * 4;
;                 float4 sh = *(const float4*)(mb + c), sc = *(const float4*)(mb + 1024 + c);
;                 f32x4 o;
;                 o[0] = (vv[rr][4 * i] - mean) * rstd * (1.f + sc.x) + sh.x;
;                 o[1] = (vv[rr][4 * i + 1] - mean) * rstd * (1.f + sc.y) + sh.y;
;                 o[2] = (vv[rr][4 * i + 2] - mean) * rstd * (1.f + sc.z) + sh.z;
;                 o[3] = (vv[rr][4 * i + 3] - mean) * rstd * (1.f + sc.w) + sh.w;
.LBB0_189:
	v_ashrrev_i32_e32 v177, 31, v176
	v_lshlrev_b64 v[128:129], 12, v[176:177]
	v_lshl_add_u64 v[140:141], v[180:181], 0, v[128:129]
	global_load_dwordx4 v[128:131], v[140:141], off
	global_load_dwordx4 v[132:135], v[140:141], off offset:1024
	global_load_dwordx4 v[136:139], v[140:141], off offset:2048
	s_nop 0
	global_load_dwordx4 v[140:143], v[140:141], off offset:3072
	v_ashrrev_i32_e32 v193, 13, v176
	v_lshl_add_u32 v237, v193, 13, v178
	v_add_u32_e32 v212, 1, v176
	v_add_u32_e32 v202, 2, v176
	v_add_u32_e32 v194, 3, v176
	v_ashrrev_i32_e32 v213, 31, v212
	v_ashrrev_i32_e32 v203, 31, v202
	v_ashrrev_i32_e32 v195, 31, v194
	v_mov_b32_e32 v187, v179
	v_mov_b32_e32 v189, v179
	v_mov_b32_e32 v191, v179
	s_waitcnt vmcnt(3)
	v_add_f32_e32 v144, 0, v128
	v_add_f32_e32 v144, v144, v129
	v_add_f32_e32 v144, v144, v130
	v_add_f32_e32 v144, v144, v131
	s_waitcnt vmcnt(2)
	v_add_f32_e32 v144, v144, v132
	v_add_f32_e32 v144, v144, v133
	v_add_f32_e32 v144, v144, v134
	v_add_f32_e32 v144, v144, v135
	s_waitcnt vmcnt(1)
	v_add_f32_e32 v144, v144, v136
	v_add_f32_e32 v144, v144, v137
	v_add_f32_e32 v144, v144, v138
	v_add_f32_e32 v144, v144, v139
	s_waitcnt vmcnt(0)
	v_add_f32_e32 v144, v144, v140
	v_add_f32_e32 v144, v144, v141
	v_add_f32_e32 v144, v144, v142
	v_add_f32_e32 v144, v144, v143
	s_nop 1
	v_add_f32_dpp v144, v144, v144 quad_perm:[1,0,3,2] row_mask:0xf bank_mask:0xf bound_ctrl:1
	s_nop 1
	v_add_f32_dpp v144, v144, v144 quad_perm:[2,3,0,1] row_mask:0xf bank_mask:0xf bound_ctrl:1
	s_nop 1
	v_add_f32_dpp v144, v144, v144 row_half_mirror row_mask:0xf bank_mask:0xf bound_ctrl:1
	s_nop 1
	v_add_f32_dpp v144, v144, v144 row_mirror row_mask:0xf bank_mask:0xf bound_ctrl:1
	s_nop 0
	v_readlane_b32 s17, v144, 16
	v_readlane_b32 s16, v144, 0
	v_readlane_b32 s18, v144, 32
	v_readlane_b32 s19, v144, 48
	v_mov_b32_e32 v144, s17
	v_add_f32_e32 v144, s16, v144
	v_add_f32_e32 v144, s18, v144
	v_add_f32_e32 v144, s19, v144
	v_mul_f32_e32 v144, 0x3a800000, v144
	v_pk_add_f32 v[146:147], v[128:129], v[144:145] op_sel_hi:[1,0] neg_lo:[0,1] neg_hi:[0,1]
	v_mul_i32_i24_e32 v128, 0x1800, v193
	v_ashrrev_i32_e32 v129, 31, v128
	v_pk_add_f32 v[222:223], v[132:133], v[144:145] op_sel_hi:[1,0] neg_lo:[0,1] neg_hi:[0,1]
	v_lshl_add_u64 v[132:133], v[128:129], 2, s[62:63]
	s_mov_b64 s[16:17], 0x1000
	v_lshl_add_u64 v[216:217], v[132:133], 0, s[16:17]
	v_lshl_add_u64 v[198:199], v[216:217], 0, v[178:179]
	v_pk_add_f32 v[148:149], v[130:131], v[144:145] op_sel_hi:[1,0] neg_lo:[0,1] neg_hi:[0,1]
	ds_read_b128 v[128:131], v237 offset:5120
	v_pk_add_f32 v[206:207], v[134:135], v[144:145] op_sel_hi:[1,0] neg_lo:[0,1] neg_hi:[0,1]
	v_pk_add_f32 v[214:215], v[136:137], v[144:145] op_sel_hi:[1,0] neg_lo:[0,1] neg_hi:[0,1]
	v_pk_add_f32 v[210:211], v[138:139], v[144:145] op_sel_hi:[1,0] neg_lo:[0,1] neg_hi:[0,1]
	v_pk_add_f32 v[200:201], v[140:141], v[144:145] op_sel_hi:[1,0] neg_lo:[0,1] neg_hi:[0,1]
	v_pk_add_f32 v[208:209], v[142:143], v[144:145] op_sel_hi:[1,0] neg_lo:[0,1] neg_hi:[0,1]
	v_lshl_add_u64 v[196:197], v[132:133], 0, v[178:179]
	s_waitcnt lgkmcnt(0)
	v_pk_add_f32 v[134:135], v[128:129], 1.0 op_sel_hi:[1,0]
	v_pk_mul_f32 v[128:129], v[146:147], v[146:147]
	v_pk_add_f32 v[136:137], v[130:131], 1.0 op_sel_hi:[1,0]
	v_add_f32_e32 v130, v128, v129
	v_pk_mul_f32 v[128:129], v[148:149], v[148:149]
	s_nop 0
	v_add_f32_e32 v128, v128, v130
	v_add_f32_e32 v130, v129, v128
	v_pk_mul_f32 v[128:129], v[222:223], v[222:223]
	s_nop 0
	v_add_f32_e32 v128, v128, v130
	v_add_f32_e32 v130, v129, v128
	v_pk_mul_f32 v[128:129], v[206:207], v[206:207]
	s_nop 0
	v_add_f32_e32 v128, v128, v130
	v_add_f32_e32 v130, v129, v128
	v_pk_mul_f32 v[128:129], v[214:215], v[214:215]
	s_nop 0
	v_add_f32_e32 v128, v128, v130
	v_add_f32_e32 v130, v129, v128
	v_pk_mul_f32 v[128:129], v[210:211], v[210:211]
	s_nop 0
	v_add_f32_e32 v128, v128, v130
	v_add_f32_e32 v130, v129, v128
	v_pk_mul_f32 v[128:129], v[200:201], v[200:201]
	s_nop 0
	v_add_f32_e32 v128, v128, v130
	v_add_f32_e32 v130, v129, v128
	v_pk_mul_f32 v[128:129], v[208:209], v[208:209]
	s_nop 0
	v_add_f32_e32 v128, v128, v130
	v_add_f32_e32 v128, v129, v128
	s_nop 1
	v_add_f32_dpp v128, v128, v128 quad_perm:[1,0,3,2] row_mask:0xf bank_mask:0xf bound_ctrl:1
	s_nop 1
	v_add_f32_dpp v128, v128, v128 quad_perm:[2,3,0,1] row_mask:0xf bank_mask:0xf bound_ctrl:1
	s_nop 1
	v_add_f32_dpp v128, v128, v128 row_half_mirror row_mask:0xf bank_mask:0xf bound_ctrl:1
	s_nop 1
	v_add_f32_dpp v128, v128, v128 row_mirror row_mask:0xf bank_mask:0xf bound_ctrl:1
	s_nop 0
	v_readlane_b32 s17, v128, 16
	v_readlane_b32 s16, v128, 0
	v_readlane_b32 s18, v128, 32
	v_readlane_b32 s19, v128, 48
	v_mov_b32_e32 v128, s17
	v_add_f32_e32 v128, s16, v128
	v_add_f32_e32 v128, s18, v128
	v_add_f32_e32 v128, s19, v128
	v_fmamk_f32 v128, v128, 0x3a800000, v232
	v_mul_f32_e32 v129, 0x4b800000, v128
	v_cmp_gt_f32_e64 s[16:17], s36, v128
	s_nop 1
	v_cndmask_b32_e64 v128, v128, v129, s[16:17]
	v_rsq_f32_e32 v128, v128
	s_nop 0
	v_mul_f32_e32 v129, 0x45800000, v128
	v_cndmask_b32_e64 v224, v128, v129, s[16:17]
	ds_read_b128 v[128:131], v237 offset:1024
	v_pk_mul_f32 v[132:133], v[146:147], v[224:225] op_sel_hi:[1,0]
	v_pk_mul_f32 v[222:223], v[222:223], v[224:225] op_sel_hi:[1,0]
	v_pk_mul_f32 v[206:207], v[206:207], v[224:225] op_sel_hi:[1,0]
	v_pk_mul_f32 v[214:215], v[214:215], v[224:225] op_sel_hi:[1,0]
	v_pk_mul_f32 v[210:211], v[210:211], v[224:225] op_sel_hi:[1,0]
	v_pk_mul_f32 v[200:201], v[200:201], v[224:225] op_sel_hi:[1,0]
	s_waitcnt lgkmcnt(0)
; DI uint2 pk4(f32x4 v) { return make_uint2(pk2(v[0], v[1]), pk2(v[2], v[3])); }
; DI void phase1(const Params& p, unsigned char* smem) {
;     ...
;             for (int i = 0; i < 4; ++i) { float4 t = *(const float4*)(p.in[0] + (size_t)(row0 + rr) * 1024 + i * 256 + lane * 4); vv[rr][4 * i] = t.x; vv[rr][4 * i + 1] = t.y; vv[rr][4 * i + 2] = t.z; vv[rr][4 * i + 3] = t.w; }
; #pragma unroll
;         for (int rr = 0; rr < 4; ++rr) {
;             const int row = row0 + rr;
;             float mean, rstd; row_stats(vv[rr], mean, rstd);
;             const float* mb = mod + (row >> 13) * 6144;
;             float ga[8];
; #pragma unroll
;             for (int j = 0; j < 8; ++j) ga[j] = 0.f;
; #pragma unroll
;             for (int i = 0; i < 4; ++i) {
;                 int c = i * 256 + lane * 4;
;                 float4 sh = *(const float4*)(mb + c), sc = *(const float4*)(mb + 1024 + c);
;                 f32x4 o;
;                 o[0] = (vv[rr][4 * i] - mean) * rstd * (1.f + sc.x) + sh.x;
;                 o[1] = (vv[rr][4 * i + 1] - mean) * rstd * (1.f + sc.y) + sh.y;
;                 o[2] = (vv[rr][4 * i + 2] - mean) * rstd * (1.f + sc.z) + sh.z;
;                 o[3] = (vv[rr][4 * i + 3] - mean) * rstd * (1.f + sc.w) + sh.w;
;                 *(uint2*)(h1 + (size_t)row * 1024 + c) = pk4(o);
; #pragma unroll
;                 for (int e = 0; e < 4; ++e) {
;                     const float4 w0 = gw0[i * 4 + e], w1 = gw1[i * 4 + e];
;                     ga[0] += o[e] * w0.x; ga[1] += o[e] * w0.y; ga[2] += o[e] * w0.z; ga[3] += o[e] * w0.w;
;                     ga[4] += o[e] * w1.x; ga[5] += o[e] * w1.y; ga[6] += o[e] * w1.z; ga[7] += o[e] * w1.w;
;                 }
	v_pk_fma_f32 v[220:221], v[134:135], v[132:133], v[128:129]
	v_pk_mul_f32 v[128:129], v[148:149], v[224:225] op_sel_hi:[1,0]
	v_lshlrev_b64 v[132:133], 12, v[194:195]
	v_pk_fma_f32 v[218:219], v[136:137], v[128:129], v[130:131]
	v_lshlrev_b64 v[128:129], 11, v[176:177]
	v_lshl_add_u64 v[226:227], v[184:185], 0, v[128:129]
	v_lshlrev_b64 v[128:129], 12, v[212:213]
	v_lshlrev_b64 v[130:131], 12, v[202:203]
	v_lshl_add_u64 v[128:129], v[180:181], 0, v[128:129]
	v_lshl_add_u64 v[130:131], v[180:181], 0, v[130:131]
	v_lshl_add_u64 v[204:205], v[180:181], 0, v[132:133]
	v_cvt_pk_bf16_f32 v228, v220, v221
	v_cvt_pk_bf16_f32 v229, v218, v219
	global_load_dwordx4 v[172:175], v[128:129], off
	global_load_dwordx4 v[168:171], v[128:129], off offset:1024
	global_load_dwordx4 v[164:167], v[128:129], off offset:2048
	global_load_dwordx4 v[160:163], v[128:129], off offset:3072
	global_load_dwordx4 v[156:159], v[130:131], off
	global_load_dwordx4 v[152:155], v[130:131], off offset:1024
	global_load_dwordx4 v[148:151], v[130:131], off offset:2048
	global_load_dwordx4 v[144:147], v[130:131], off offset:3072
	global_load_dwordx4 v[140:143], v[204:205], off
	global_load_dwordx4 v[136:139], v[204:205], off offset:1024
	global_load_dwordx4 v[132:135], v[204:205], off offset:2048
	s_nop 0
	global_load_dwordx4 v[128:131], v[204:205], off offset:3072
	v_lshl_add_u64 v[204:205], v[216:217], 0, v[186:187]
	global_store_dwordx2 v[226:227], v[228:229], off
	ds_read_b128 v[238:241], v237 offset:6144
	v_fma_f32 v177, v0, v220, 0
	v_fmac_f32_e32 v177, v8, v221
	v_fmac_f32_e32 v177, v16, v218
	v_fmac_f32_e32 v177, v24, v219
	v_fma_f32 v187, v1, v220, 0
	v_fmac_f32_e32 v187, v9, v221
	v_fmac_f32_e32 v187, v17, v218
	v_fmac_f32_e32 v187, v25, v219
	s_waitcnt lgkmcnt(0)
	v_pk_add_f32 v[228:229], v[238:239], 1.0 op_sel_hi:[1,0]
	v_pk_add_f32 v[242:243], v[240:241], 1.0 op_sel_hi:[1,0]
	ds_read_b128 v[238:241], v237 offset:2048
	s_waitcnt lgkmcnt(0)
	v_pk_fma_f32 v[228:229], v[222:223], v[228:229], v[238:239]
	v_pk_fma_f32 v[222:223], v[206:207], v[242:243], v[240:241]
	v_cvt_pk_bf16_f32 v206, v228, v229
	v_cvt_pk_bf16_f32 v207, v222, v223
	global_store_dwordx2 v[226:227], v[206:207], off offset:512
	v_lshl_add_u64 v[206:207], v[216:217], 0, v[188:189]
	ds_read_b128 v[238:241], v237 offset:7168
	v_fmac_f32_e32 v177, v32, v228
	v_fmac_f32_e32 v177, v40, v229
	v_fmac_f32_e32 v177, v48, v222
	v_fmac_f32_e32 v177, v56, v223
	v_fma_f32 v189, v2, v220, 0
	v_fmac_f32_e32 v187, v33, v228
	v_fmac_f32_e32 v189, v10, v221
	v_fmac_f32_e32 v187, v41, v229
	v_fmac_f32_e32 v189, v18, v218
	v_fmac_f32_e32 v187, v49, v222
	v_fmac_f32_e32 v189, v26, v219
	v_fmac_f32_e32 v187, v57, v223
	v_fmac_f32_e32 v189, v34, v228
	v_fmac_f32_e32 v189, v42, v229
	v_fmac_f32_e32 v189, v50, v222
	v_fmac_f32_e32 v189, v58, v223
	s_waitcnt lgkmcnt(0)
	v_pk_add_f32 v[242:243], v[238:239], 1.0 op_sel_hi:[1,0]
	v_pk_add_f32 v[244:245], v[240:241], 1.0 op_sel_hi:[1,0]
	ds_read_b128 v[238:241], v237 offset:3072
	s_waitcnt lgkmcnt(0)
	v_pk_fma_f32 v[238:239], v[214:215], v[242:243], v[238:239]
	v_pk_fma_f32 v[210:211], v[210:211], v[244:245], v[240:241]
	v_pk_mul_f32 v[240:241], v[208:209], v[224:225] op_sel_hi:[1,0]
	v_cvt_pk_bf16_f32 v208, v238, v239
	v_cvt_pk_bf16_f32 v209, v210, v211
	global_store_dwordx2 v[226:227], v[208:209], off offset:1024
	v_lshl_add_u64 v[208:209], v[216:217], 0, v[190:191]
	ds_read_b128 v[214:217], v237 offset:8192
	v_fmac_f32_e32 v177, v64, v238
	v_fmac_f32_e32 v177, v72, v239
	v_fmac_f32_e32 v177, v80, v210
	v_fmac_f32_e32 v177, v88, v211
	v_fma_f32 v191, v3, v220, 0
	v_fmac_f32_e32 v187, v65, v238
	v_fmac_f32_e32 v191, v11, v221
	v_fmac_f32_e32 v187, v73, v239
	v_fmac_f32_e32 v191, v19, v218
	v_fmac_f32_e32 v187, v81, v210
	v_fmac_f32_e32 v191, v27, v219
	v_fmac_f32_e32 v187, v89, v211
	v_fmac_f32_e32 v191, v35, v228
	v_fmac_f32_e32 v189, v66, v238
	v_fmac_f32_e32 v191, v43, v229
	v_fmac_f32_e32 v189, v74, v239
	v_fmac_f32_e32 v191, v51, v222
	v_fmac_f32_e32 v189, v82, v210
	v_fmac_f32_e32 v191, v59, v223
	v_fmac_f32_e32 v189, v90, v211
	v_fmac_f32_e32 v191, v67, v238
	v_fmac_f32_e32 v191, v75, v239
	v_fmac_f32_e32 v191, v83, v210
	v_fmac_f32_e32 v191, v91, v211
	v_fma_f32 v224, v6, v220, 0
	v_fmac_f32_e32 v224, v14, v221
	v_fmac_f32_e32 v224, v22, v218
	v_fmac_f32_e32 v224, v30, v219
	v_fmac_f32_e32 v224, v38, v228
	v_fmac_f32_e32 v224, v46, v229
	v_fmac_f32_e32 v224, v54, v222
	v_fmac_f32_e32 v224, v62, v223
	v_fmac_f32_e32 v224, v70, v238
	v_fmac_f32_e32 v224, v78, v239
	v_fmac_f32_e32 v224, v86, v210
	v_fmac_f32_e32 v224, v94, v211
	s_waitcnt lgkmcnt(0)
	v_pk_add_f32 v[242:243], v[214:215], 1.0 op_sel_hi:[1,0]
	v_pk_add_f32 v[244:245], v[216:217], 1.0 op_sel_hi:[1,0]
	ds_read_b128 v[214:217], v237 offset:4096
	s_waitcnt vmcnt(3) lgkmcnt(0)
; DI void phase1(const Params& p, unsigned char* smem) {
;     ...
; #pragma unroll
;                 for (int e = 0; e < 4; ++e) {
;                     const float4 w0 = gw0[i * 4 + e], w1 = gw1[i * 4 + e];
;                     ga[0] += o[e] * w0.x; ga[1] += o[e] * w0.y; ga[2] += o[e] * w0.z; ga[3] += o[e] * w0.w;
;                     ga[4] += o[e] * w1.x; ga[5] += o[e] * w1.y; ga[6] += o[e] * w1.z; ga[7] += o[e] * w1.w;
;                 }
;             }
; #pragma unroll
;             for (int j = 0; j < 8; ++j) ga[j] = wsum(ga[j]);
;             if (lane < 8) {
;                 float val = ga[0];
; #pragma unroll
;                 for (int j = 1; j < 8; ++j) val = (lane == j) ? ga[j] : val;
;                 val += p.in[5][2048 + lane];
;                 const int b = row >> 13, sidx = row & 8191;
;                 if (lane < 4) ig[(size_t)(b * 4 + lane) * 8192 + sidx] = val;
	v_pk_fma_f32 v[200:201], v[200:201], v[242:243], v[214:215]
	s_nop 0
	v_fmac_f32_e32 v177, v96, v200
	v_pk_fma_f32 v[214:215], v[240:241], v[244:245], v[216:217]
	v_fmac_f32_e32 v177, v104, v201
	v_fmac_f32_e32 v177, v112, v214
	v_cvt_pk_bf16_f32 v216, v200, v201
	v_cvt_pk_bf16_f32 v217, v214, v215
	v_fmac_f32_e32 v177, v120, v215
	global_store_dwordx2 v[226:227], v[216:217], off offset:1536
	v_fma_f32 v216, v4, v220, 0
	v_fmac_f32_e32 v187, v97, v200
	v_add_f32_dpp v177, v177, v177 quad_perm:[1,0,3,2] row_mask:0xf bank_mask:0xf bound_ctrl:1
	v_fmac_f32_e32 v216, v12, v221
	v_fmac_f32_e32 v187, v105, v201
	v_add_f32_dpp v177, v177, v177 quad_perm:[2,3,0,1] row_mask:0xf bank_mask:0xf bound_ctrl:1
	v_fmac_f32_e32 v216, v20, v218
	v_fmac_f32_e32 v187, v113, v214
	v_add_f32_dpp v177, v177, v177 row_half_mirror row_mask:0xf bank_mask:0xf bound_ctrl:1
	v_fmac_f32_e32 v216, v28, v219
	v_fmac_f32_e32 v187, v121, v215
	v_add_f32_dpp v177, v177, v177 row_mirror row_mask:0xf bank_mask:0xf bound_ctrl:1
	v_fma_f32 v217, v5, v220, 0
	v_fmac_f32_e32 v216, v36, v228
	v_fmac_f32_e32 v189, v98, v200
	v_readlane_b32 s16, v177, 0
	v_readlane_b32 s31, v177, 16
	v_readlane_b32 s17, v177, 32
	v_readlane_b32 s30, v177, 48
	v_add_f32_dpp v177, v187, v187 quad_perm:[1,0,3,2] row_mask:0xf bank_mask:0xf bound_ctrl:1
	v_fmac_f32_e32 v217, v13, v221
	v_fmac_f32_e32 v216, v44, v229
	v_fmac_f32_e32 v189, v106, v201
	v_add_f32_dpp v177, v177, v177 quad_perm:[2,3,0,1] row_mask:0xf bank_mask:0xf bound_ctrl:1
	v_fmac_f32_e32 v217, v21, v218
	v_fmac_f32_e32 v216, v52, v222
	v_fmac_f32_e32 v189, v114, v214
	v_add_f32_dpp v177, v177, v177 row_half_mirror row_mask:0xf bank_mask:0xf bound_ctrl:1
	v_fmac_f32_e32 v217, v29, v219
	v_fmac_f32_e32 v216, v60, v223
	v_fmac_f32_e32 v189, v122, v215
	v_add_f32_dpp v177, v177, v177 row_mirror row_mask:0xf bank_mask:0xf bound_ctrl:1
	v_fmac_f32_e32 v217, v37, v228
	v_fmac_f32_e32 v216, v68, v238
	v_fmac_f32_e32 v191, v99, v200
	v_readlane_b32 s34, v177, 0
	v_readlane_b32 s42, v177, 16
	v_readlane_b32 s35, v177, 32
	v_readlane_b32 s41, v177, 48
	v_add_f32_dpp v177, v189, v189 quad_perm:[1,0,3,2] row_mask:0xf bank_mask:0xf bound_ctrl:1
	v_fmac_f32_e32 v217, v45, v229
	v_fmac_f32_e32 v216, v76, v239
	v_fmac_f32_e32 v191, v107, v201
	v_add_f32_dpp v177, v177, v177 quad_perm:[2,3,0,1] row_mask:0xf bank_mask:0xf bound_ctrl:1
	v_fmac_f32_e32 v217, v53, v222
	v_fmac_f32_e32 v216, v84, v210
	v_fmac_f32_e32 v191, v115, v214
	v_add_f32_dpp v177, v177, v177 row_half_mirror row_mask:0xf bank_mask:0xf bound_ctrl:1
	v_fmac_f32_e32 v217, v61, v223
	v_fmac_f32_e32 v216, v92, v211
	v_fmac_f32_e32 v191, v123, v215
	v_add_f32_dpp v177, v177, v177 row_mirror row_mask:0xf bank_mask:0xf bound_ctrl:1
	v_fma_f32 v220, v7, v220, 0
	v_fmac_f32_e32 v217, v69, v238
	v_fmac_f32_e32 v216, v100, v200
	v_readlane_b32 s43, v177, 0
	v_readlane_b32 s46, v177, 16
	v_readlane_b32 s44, v177, 32
	v_readlane_b32 s45, v177, 48
	v_add_f32_dpp v177, v191, v191 quad_perm:[1,0,3,2] row_mask:0xf bank_mask:0xf bound_ctrl:1
	v_fmac_f32_e32 v220, v15, v221
	v_fmac_f32_e32 v217, v77, v239
	v_fmac_f32_e32 v216, v108, v201
	v_add_f32_dpp v177, v177, v177 quad_perm:[2,3,0,1] row_mask:0xf bank_mask:0xf bound_ctrl:1
	v_fmac_f32_e32 v220, v23, v218
	v_fmac_f32_e32 v217, v85, v210
	v_fmac_f32_e32 v216, v116, v214
	v_add_f32_dpp v177, v177, v177 row_half_mirror row_mask:0xf bank_mask:0xf bound_ctrl:1
	v_fmac_f32_e32 v220, v31, v219
	v_fmac_f32_e32 v217, v93, v211
	v_fmac_f32_e32 v216, v124, v215
	v_add_f32_dpp v177, v177, v177 row_mirror row_mask:0xf bank_mask:0xf bound_ctrl:1
	v_fmac_f32_e32 v220, v39, v228
	v_fmac_f32_e32 v217, v101, v200
	v_readlane_b32 s47, v177, 0
	v_readlane_b32 s50, v177, 16
	v_readlane_b32 s48, v177, 32
	v_readlane_b32 s49, v177, 48
	v_add_f32_dpp v177, v216, v216 quad_perm:[1,0,3,2] row_mask:0xf bank_mask:0xf bound_ctrl:1
	v_fmac_f32_e32 v220, v47, v229
	v_fmac_f32_e32 v217, v109, v201
	v_add_f32_dpp v177, v177, v177 quad_perm:[2,3,0,1] row_mask:0xf bank_mask:0xf bound_ctrl:1
	v_fmac_f32_e32 v220, v55, v222
	v_fmac_f32_e32 v217, v117, v214
	v_add_f32_dpp v177, v177, v177 row_half_mirror row_mask:0xf bank_mask:0xf bound_ctrl:1
	v_fmac_f32_e32 v220, v63, v223
	v_fmac_f32_e32 v217, v125, v215
	v_add_f32_dpp v177, v177, v177 row_mirror row_mask:0xf bank_mask:0xf bound_ctrl:1
	v_fmac_f32_e32 v220, v71, v238
	v_fmac_f32_e32 v224, v102, v200
	v_readlane_b32 s51, v177, 0
	v_readlane_b32 s55, v177, 16
	v_readlane_b32 s52, v177, 32
	v_readlane_b32 s53, v177, 48
	v_add_f32_dpp v177, v217, v217 quad_perm:[1,0,3,2] row_mask:0xf bank_mask:0xf bound_ctrl:1
	v_fmac_f32_e32 v220, v79, v239
	v_fmac_f32_e32 v224, v110, v201
	v_add_f32_dpp v177, v177, v177 quad_perm:[2,3,0,1] row_mask:0xf bank_mask:0xf bound_ctrl:1
	v_fmac_f32_e32 v220, v87, v210
	v_fmac_f32_e32 v224, v118, v214
	v_add_f32_dpp v177, v177, v177 row_half_mirror row_mask:0xf bank_mask:0xf bound_ctrl:1
	v_fmac_f32_e32 v220, v95, v211
	v_fmac_f32_e32 v224, v126, v215
	v_add_f32_dpp v177, v177, v177 row_mirror row_mask:0xf bank_mask:0xf bound_ctrl:1
	v_fmac_f32_e32 v220, v103, v200
	v_readlane_b32 s56, v177, 0
	v_readlane_b32 s73, v177, 16
	v_readlane_b32 s57, v177, 32
	v_readlane_b32 s72, v177, 48
	v_add_f32_dpp v177, v224, v224 quad_perm:[1,0,3,2] row_mask:0xf bank_mask:0xf bound_ctrl:1
	v_fmac_f32_e32 v220, v111, v201
	v_fmac_f32_e32 v220, v119, v214
	v_add_f32_dpp v177, v177, v177 quad_perm:[2,3,0,1] row_mask:0xf bank_mask:0xf bound_ctrl:1
	v_fmac_f32_e32 v220, v127, v215
	s_nop 0
	v_add_f32_dpp v177, v177, v177 row_half_mirror row_mask:0xf bank_mask:0xf bound_ctrl:1
	s_nop 1
	v_add_f32_dpp v177, v177, v177 row_mirror row_mask:0xf bank_mask:0xf bound_ctrl:1
	s_nop 0
	v_readlane_b32 s74, v177, 0
	v_readlane_b32 s83, v177, 16
	v_readlane_b32 s75, v177, 32
	v_readlane_b32 s82, v177, 48
	v_add_f32_dpp v177, v220, v220 quad_perm:[1,0,3,2] row_mask:0xf bank_mask:0xf bound_ctrl:1
	s_nop 1
	v_add_f32_dpp v177, v177, v177 quad_perm:[2,3,0,1] row_mask:0xf bank_mask:0xf bound_ctrl:1
	s_nop 1
	v_add_f32_dpp v177, v177, v177 row_half_mirror row_mask:0xf bank_mask:0xf bound_ctrl:1
	s_nop 1
	v_add_f32_dpp v177, v177, v177 row_mirror row_mask:0xf bank_mask:0xf bound_ctrl:1
	s_nop 0
	v_readlane_b32 s84, v177, 0
	v_readlane_b32 s87, v177, 16
	v_readlane_b32 s85, v177, 32
	v_readlane_b32 s86, v177, 48
	v_lshlrev_b32_e32 v177, 2, v193
	v_add_u32_e32 v200, v231, v177
	v_add_u32_e32 v210, v177, v230
	v_ashrrev_i32_e32 v201, 31, v200
	v_ashrrev_i32_e32 v211, 31, v210
	v_lshlrev_b64 v[200:201], 15, v[200:201]
	v_lshlrev_b64 v[210:211], 15, v[210:211]
	v_lshl_add_u64 v[200:201], s[20:21], 0, v[200:201]
	v_lshl_add_u64 v[210:211], s[88:89], 0, v[210:211]
	s_and_saveexec_b64 s[28:29], vcc
	s_cbranch_execz .LBB0_197
; DI float logsig(float x) { return (x < 0.f) ? (x - log1pf(__expf(x))) : (-log1pf(__expf(-x))); }
; DI void row_stats(const float (&v)[16], float& mean, float& rstd) {
;     float s = 0.f;
; #pragma unroll
;     for (int i = 0; i < 16; ++i) s += v[i];
;     mean = wsum(s) * (1.f / 1024.f);
;     float q = 0.f;
; #pragma unroll
;     for (int i = 0; i < 16; ++i) { float d = v[i] - mean; q += d * d; }
;     rstd = rsqrtf(wsum(q) * (1.f / 1024.f) + 1e-5f);
; }
; DI void phase1(const Params& p, unsigned char* smem) {
;     ...
;             if (lane < 8) {
;                 float val = ga[0];
; #pragma unroll
;                 for (int j = 1; j < 8; ++j) val = (lane == j) ? ga[j] : val;
;                 val += p.in[5][2048 + lane];
;                 const int b = row >> 13, sidx = row & 8191;
;                 if (lane < 4) ig[(size_t)(b * 4 + lane) * 8192 + sidx] = val;
;                 else lf[(size_t)(b * 4 + lane - 4) * 8192 + sidx] = logsig(val);
;             }
	v_mov_b32_e32 v215, s42
	v_mov_b32_e32 v216, s31
	v_mov_b32_e32 v214, s46
	v_add_f32_e32 v215, s34, v215
	v_add_f32_e32 v216, s16, v216
	v_mov_b32_e32 v193, s50
	v_add_f32_e32 v214, s43, v214
	v_add_f32_e32 v215, s35, v215
	v_add_f32_e32 v216, s17, v216
	v_mov_b32_e32 v191, s55
	v_add_f32_e32 v193, s47, v193
	v_add_f32_e32 v214, s44, v214
	v_add_f32_e32 v215, s41, v215
	v_add_f32_e32 v216, s30, v216
	v_mov_b32_e32 v189, s73
	v_add_f32_e32 v191, s51, v191
	v_add_f32_e32 v193, s48, v193
	v_add_f32_e32 v214, s45, v214
	v_cndmask_b32_e64 v215, v216, v215, s[0:1]
	v_mov_b32_e32 v187, s83
	v_add_f32_e32 v189, s56, v189
	v_add_f32_e32 v191, s52, v191
	v_add_f32_e32 v193, s49, v193
	v_cndmask_b32_e64 v214, v215, v214, s[14:15]
	v_mov_b32_e32 v177, s87
	v_add_f32_e32 v187, s74, v187
	v_add_f32_e32 v189, s57, v189
	v_add_f32_e32 v191, s53, v191
	v_cndmask_b32_e64 v193, v214, v193, s[4:5]
	v_add_f32_e32 v177, s84, v177
	v_add_f32_e32 v187, s75, v187
	v_add_f32_e32 v189, s72, v189
	v_cndmask_b32_e64 v191, v193, v191, s[6:7]
	v_add_f32_e32 v177, s85, v177
	v_add_f32_e32 v187, s82, v187
	v_cndmask_b32_e64 v189, v191, v189, s[8:9]
	v_add_f32_e32 v177, s86, v177
	v_cndmask_b32_e64 v187, v189, v187, s[10:11]
	v_cndmask_b32_e64 v177, v187, v177, s[12:13]
	ds_write_b32 v253, v177 offset:0
.LBB0_197:
	s_or_b64 exec, exec, s[28:29]
	ds_read_b128 v[214:217], v237 offset:5120
	ds_read_b128 v[218:221], v237 offset:1024
	v_add_f32_e32 v177, 0, v172
	v_add_f32_e32 v177, v177, v173
	v_add_f32_e32 v177, v177, v174
	v_add_f32_e32 v177, v177, v175
	v_add_f32_e32 v177, v177, v168
	v_add_f32_e32 v177, v177, v169
	v_add_f32_e32 v177, v177, v170
	v_add_f32_e32 v177, v177, v171
	v_add_f32_e32 v177, v177, v164
	v_add_f32_e32 v177, v177, v165
	v_add_f32_e32 v177, v177, v166
	v_add_f32_e32 v177, v177, v167
	v_add_f32_e32 v177, v177, v160
	v_add_f32_e32 v177, v177, v161
	v_add_f32_e32 v177, v177, v162
	v_add_f32_e32 v177, v177, v163
	v_lshlrev_b64 v[222:223], 11, v[212:213]
	s_nop 0
	v_add_f32_dpp v177, v177, v177 quad_perm:[1,0,3,2] row_mask:0xf bank_mask:0xf bound_ctrl:1
	s_nop 1
	v_add_f32_dpp v177, v177, v177 quad_perm:[2,3,0,1] row_mask:0xf bank_mask:0xf bound_ctrl:1
	s_nop 1
	v_add_f32_dpp v177, v177, v177 row_half_mirror row_mask:0xf bank_mask:0xf bound_ctrl:1
	s_nop 1
	v_add_f32_dpp v177, v177, v177 row_mirror row_mask:0xf bank_mask:0xf bound_ctrl:1
	s_nop 0
	v_readlane_b32 s17, v177, 16
	v_readlane_b32 s16, v177, 0
	v_readlane_b32 s18, v177, 32
	v_readlane_b32 s19, v177, 48
	v_mov_b32_e32 v177, s17
	v_add_f32_e32 v177, s16, v177
	v_add_f32_e32 v177, s18, v177
	v_add_f32_e32 v177, s19, v177
	v_mul_f32_e32 v224, 0x3a800000, v177
	v_pk_add_f32 v[172:173], v[172:173], v[224:225] op_sel_hi:[1,0] neg_lo:[0,1] neg_hi:[0,1]
	v_pk_add_f32 v[174:175], v[174:175], v[224:225] op_sel_hi:[1,0] neg_lo:[0,1] neg_hi:[0,1]
	v_pk_add_f32 v[240:241], v[164:165], v[224:225] op_sel_hi:[1,0] neg_lo:[0,1] neg_hi:[0,1]
	v_pk_add_f32 v[164:165], v[162:163], v[224:225] op_sel_hi:[1,0] neg_lo:[0,1] neg_hi:[0,1]
	v_pk_mul_f32 v[162:163], v[172:173], v[172:173]
	v_pk_add_f32 v[238:239], v[166:167], v[224:225] op_sel_hi:[1,0] neg_lo:[0,1] neg_hi:[0,1]
	v_pk_add_f32 v[166:167], v[160:161], v[224:225] op_sel_hi:[1,0] neg_lo:[0,1] neg_hi:[0,1]
	v_pk_mul_f32 v[160:161], v[174:175], v[174:175]
	v_add_f32_e32 v162, v162, v163
	v_pk_add_f32 v[228:229], v[168:169], v[224:225] op_sel_hi:[1,0] neg_lo:[0,1] neg_hi:[0,1]
	v_add_f32_e32 v160, v160, v162
	v_pk_add_f32 v[226:227], v[170:171], v[224:225] op_sel_hi:[1,0] neg_lo:[0,1] neg_hi:[0,1]
	v_pk_mul_f32 v[170:171], v[228:229], v[228:229]
	v_add_f32_e32 v160, v161, v160
	v_add_f32_e32 v160, v170, v160
	v_pk_mul_f32 v[168:169], v[226:227], v[226:227]
	v_add_f32_e32 v160, v171, v160
	v_add_f32_e32 v160, v168, v160
	v_pk_mul_f32 v[244:245], v[240:241], v[240:241]
	v_add_f32_e32 v160, v169, v160
	v_add_f32_e32 v160, v244, v160
	v_pk_mul_f32 v[242:243], v[238:239], v[238:239]
	v_add_f32_e32 v160, v245, v160
	v_add_f32_e32 v160, v242, v160
	v_pk_mul_f32 v[248:249], v[166:167], v[166:167]
	v_add_f32_e32 v160, v243, v160
	v_add_f32_e32 v160, v248, v160
	v_pk_mul_f32 v[246:247], v[164:165], v[164:165]
	v_add_f32_e32 v160, v249, v160
	v_add_f32_e32 v160, v246, v160
	v_add_f32_e32 v160, v247, v160
	s_waitcnt lgkmcnt(1)
	v_pk_add_f32 v[162:163], v[214:215], 1.0 op_sel_hi:[1,0]
	v_add_f32_dpp v160, v160, v160 quad_perm:[1,0,3,2] row_mask:0xf bank_mask:0xf bound_ctrl:1
	v_pk_add_f32 v[170:171], v[216:217], 1.0 op_sel_hi:[1,0]
	s_nop 0
	v_add_f32_dpp v160, v160, v160 quad_perm:[2,3,0,1] row_mask:0xf bank_mask:0xf bound_ctrl:1
	s_nop 1
	v_add_f32_dpp v160, v160, v160 row_half_mirror row_mask:0xf bank_mask:0xf bound_ctrl:1
	s_nop 1
	v_add_f32_dpp v160, v160, v160 row_mirror row_mask:0xf bank_mask:0xf bound_ctrl:1
	s_nop 0
	v_readlane_b32 s17, v160, 16
	v_readlane_b32 s16, v160, 0
	v_readlane_b32 s18, v160, 32
	v_readlane_b32 s19, v160, 48
	v_mov_b32_e32 v160, s17
	v_add_f32_e32 v160, s16, v160
	v_add_f32_e32 v160, s18, v160
	v_add_f32_e32 v160, s19, v160
	v_fmamk_f32 v160, v160, 0x3a800000, v232
	v_mul_f32_e32 v161, 0x4b800000, v160
	v_cmp_gt_f32_e64 s[16:17], s36, v160
	s_nop 1
	v_cndmask_b32_e64 v160, v160, v161, s[16:17]
	v_rsq_f32_e32 v168, v160
	v_lshl_add_u64 v[160:161], v[184:185], 0, v[222:223]
	v_mul_f32_e32 v169, 0x45800000, v168
	v_cndmask_b32_e64 v222, v168, v169, s[16:17]
	v_pk_mul_f32 v[168:169], v[172:173], v[222:223] op_sel_hi:[1,0]
	s_waitcnt lgkmcnt(0)
; DI uint2 pk4(f32x4 v) { return make_uint2(pk2(v[0], v[1]), pk2(v[2], v[3])); }
; DI void phase1(const Params& p, unsigned char* smem) {
;     ...
;             for (int i = 0; i < 4; ++i) {
;                 int c = i * 256 + lane * 4;
;                 float4 sh = *(const float4*)(mb + c), sc = *(const float4*)(mb + 1024 + c);
;                 f32x4 o;
;                 o[0] = (vv[rr][4 * i] - mean) * rstd * (1.f + sc.x) + sh.x;
;                 o[1] = (vv[rr][4 * i + 1] - mean) * rstd * (1.f + sc.y) + sh.y;
;                 o[2] = (vv[rr][4 * i + 2] - mean) * rstd * (1.f + sc.z) + sh.z;
;                 o[3] = (vv[rr][4 * i + 3] - mean) * rstd * (1.f + sc.w) + sh.w;
;                 *(uint2*)(h1 + (size_t)row * 1024 + c) = pk4(o);
; #pragma unroll
;                 for (int e = 0; e < 4; ++e) {
;                     const float4 w0 = gw0[i * 4 + e], w1 = gw1[i * 4 + e];
;                     ga[0] += o[e] * w0.x; ga[1] += o[e] * w0.y; ga[2] += o[e] * w0.z; ga[3] += o[e] * w0.w;
;                     ga[4] += o[e] * w1.x; ga[5] += o[e] * w1.y; ga[6] += o[e] * w1.z; ga[7] += o[e] * w1.w;
;                 }
	v_pk_fma_f32 v[168:169], v[162:163], v[168:169], v[218:219]
	v_pk_mul_f32 v[162:163], v[174:175], v[222:223] op_sel_hi:[1,0]
	v_pk_mul_f32 v[174:175], v[228:229], v[222:223] op_sel_hi:[1,0]
	v_pk_fma_f32 v[162:163], v[170:171], v[162:163], v[220:221]
	v_cvt_pk_bf16_f32 v170, v168, v169
	v_cvt_pk_bf16_f32 v171, v162, v163
	global_store_dwordx2 v[160:161], v[170:171], off
	ds_read_b128 v[170:173], v237 offset:6144
	s_nop 0
	ds_read_b128 v[214:217], v237 offset:2048
	v_pk_mul_f32 v[218:219], v[226:227], v[222:223] op_sel_hi:[1,0]
	v_pk_mul_f32 v[220:221], v[240:241], v[222:223] op_sel_hi:[1,0]
	v_pk_mul_f32 v[226:227], v[238:239], v[222:223] op_sel_hi:[1,0]
	v_pk_mul_f32 v[228:229], v[166:167], v[222:223] op_sel_hi:[1,0]
	v_pk_mul_f32 v[222:223], v[164:165], v[222:223] op_sel_hi:[1,0]
	v_fma_f32 v177, v0, v168, 0
	v_fma_f32 v187, v1, v168, 0
	v_fma_f32 v189, v2, v168, 0
	v_fma_f32 v191, v3, v168, 0
	v_fma_f32 v193, v4, v168, 0
	v_fma_f32 v213, v5, v168, 0
	v_fma_f32 v224, v6, v168, 0
	v_fma_f32 v225, v7, v168, 0
	v_fmac_f32_e32 v177, v8, v169
	v_fmac_f32_e32 v187, v9, v169
	v_fmac_f32_e32 v189, v10, v169
	v_fmac_f32_e32 v191, v11, v169
	v_fmac_f32_e32 v193, v12, v169
	v_fmac_f32_e32 v213, v13, v169
	v_fmac_f32_e32 v224, v14, v169
	v_fmac_f32_e32 v225, v15, v169
	v_fmac_f32_e32 v177, v16, v162
	v_fmac_f32_e32 v187, v17, v162
	v_fmac_f32_e32 v189, v18, v162
	v_fmac_f32_e32 v191, v19, v162
	v_fmac_f32_e32 v193, v20, v162
	v_fmac_f32_e32 v213, v21, v162
	v_fmac_f32_e32 v224, v22, v162
	v_fmac_f32_e32 v225, v23, v162
	v_fmac_f32_e32 v177, v24, v163
	v_fmac_f32_e32 v187, v25, v163
	v_fmac_f32_e32 v189, v26, v163
	v_fmac_f32_e32 v191, v27, v163
	v_fmac_f32_e32 v193, v28, v163
	v_fmac_f32_e32 v213, v29, v163
	v_fmac_f32_e32 v224, v30, v163
	v_fmac_f32_e32 v225, v31, v163
	s_waitcnt lgkmcnt(1)
	v_pk_add_f32 v[170:171], v[170:171], 1.0 op_sel_hi:[1,0]
	v_pk_add_f32 v[172:173], v[172:173], 1.0 op_sel_hi:[1,0]
	s_waitcnt lgkmcnt(0)
	v_pk_fma_f32 v[174:175], v[174:175], v[170:171], v[214:215]
	v_pk_fma_f32 v[218:219], v[218:219], v[172:173], v[216:217]
	v_cvt_pk_bf16_f32 v170, v174, v175
	v_cvt_pk_bf16_f32 v171, v218, v219
	global_store_dwordx2 v[160:161], v[170:171], off offset:512
	ds_read_b128 v[170:173], v237 offset:7168
	s_nop 0
	ds_read_b128 v[214:217], v237 offset:3072
	v_fmac_f32_e32 v177, v32, v174
	v_fmac_f32_e32 v187, v33, v174
	v_fmac_f32_e32 v189, v34, v174
	v_fmac_f32_e32 v191, v35, v174
	v_fmac_f32_e32 v193, v36, v174
	v_fmac_f32_e32 v213, v37, v174
	v_fmac_f32_e32 v224, v38, v174
	v_fmac_f32_e32 v225, v39, v174
	v_fmac_f32_e32 v177, v40, v175
	v_fmac_f32_e32 v187, v41, v175
	v_fmac_f32_e32 v189, v42, v175
	v_fmac_f32_e32 v191, v43, v175
	v_fmac_f32_e32 v193, v44, v175
	v_fmac_f32_e32 v213, v45, v175
	v_fmac_f32_e32 v224, v46, v175
	v_fmac_f32_e32 v225, v47, v175
	v_fmac_f32_e32 v177, v48, v218
	v_fmac_f32_e32 v187, v49, v218
	v_fmac_f32_e32 v189, v50, v218
	v_fmac_f32_e32 v191, v51, v218
	v_fmac_f32_e32 v193, v52, v218
	v_fmac_f32_e32 v213, v53, v218
	v_fmac_f32_e32 v224, v54, v218
	v_fmac_f32_e32 v225, v55, v218
	v_fmac_f32_e32 v177, v56, v219
	v_fmac_f32_e32 v187, v57, v219
	v_fmac_f32_e32 v189, v58, v219
	v_fmac_f32_e32 v191, v59, v219
	v_fmac_f32_e32 v193, v60, v219
	v_fmac_f32_e32 v213, v61, v219
	v_fmac_f32_e32 v224, v62, v219
	v_fmac_f32_e32 v225, v63, v219
	s_waitcnt lgkmcnt(1)
	v_pk_add_f32 v[164:165], v[170:171], 1.0 op_sel_hi:[1,0]
	v_pk_add_f32 v[166:167], v[172:173], 1.0 op_sel_hi:[1,0]
	s_waitcnt lgkmcnt(0)
	v_pk_fma_f32 v[172:173], v[220:221], v[164:165], v[214:215]
	v_pk_fma_f32 v[214:215], v[226:227], v[166:167], v[216:217]
	v_cvt_pk_bf16_f32 v164, v172, v173
	v_cvt_pk_bf16_f32 v165, v214, v215
	global_store_dwordx2 v[160:161], v[164:165], off offset:1024
	ds_read_b128 v[164:167], v237 offset:4096
	s_nop 0
	ds_read_b128 v[168:171], v237 offset:8192
	v_fmac_f32_e32 v177, v64, v172
	v_fmac_f32_e32 v187, v65, v172
	v_fmac_f32_e32 v189, v66, v172
	v_fmac_f32_e32 v191, v67, v172
	v_fmac_f32_e32 v193, v68, v172
	v_fmac_f32_e32 v213, v69, v172
	v_fmac_f32_e32 v224, v70, v172
	v_fmac_f32_e32 v225, v71, v172
	v_fmac_f32_e32 v177, v72, v173
	v_fmac_f32_e32 v187, v73, v173
	v_fmac_f32_e32 v189, v74, v173
	v_fmac_f32_e32 v191, v75, v173
	v_fmac_f32_e32 v193, v76, v173
	v_fmac_f32_e32 v213, v77, v173
	v_fmac_f32_e32 v224, v78, v173
	v_fmac_f32_e32 v225, v79, v173
	v_fmac_f32_e32 v177, v80, v214
	v_fmac_f32_e32 v187, v81, v214
	v_fmac_f32_e32 v189, v82, v214
	v_fmac_f32_e32 v191, v83, v214
	v_fmac_f32_e32 v193, v84, v214
	v_fmac_f32_e32 v213, v85, v214
	v_fmac_f32_e32 v224, v86, v214
	v_fmac_f32_e32 v225, v87, v214
	v_fmac_f32_e32 v177, v88, v215
	v_fmac_f32_e32 v187, v89, v215
	v_fmac_f32_e32 v189, v90, v215
	v_fmac_f32_e32 v191, v91, v215
	v_fmac_f32_e32 v193, v92, v215
	v_fmac_f32_e32 v213, v93, v215
	v_fmac_f32_e32 v224, v94, v215
	v_fmac_f32_e32 v225, v95, v215
	s_waitcnt lgkmcnt(0)
; DI void phase1(const Params& p, unsigned char* smem) {
;     ...
; #pragma unroll
;                 for (int e = 0; e < 4; ++e) {
;                     const float4 w0 = gw0[i * 4 + e], w1 = gw1[i * 4 + e];
;                     ga[0] += o[e] * w0.x; ga[1] += o[e] * w0.y; ga[2] += o[e] * w0.z; ga[3] += o[e] * w0.w;
;                     ga[4] += o[e] * w1.x; ga[5] += o[e] * w1.y; ga[6] += o[e] * w1.z; ga[7] += o[e] * w1.w;
;                 }
;             }
; #pragma unroll
;             for (int j = 0; j < 8; ++j) ga[j] = wsum(ga[j]);
;             if (lane < 8) {
;                 float val = ga[0];
; #pragma unroll
;                 for (int j = 1; j < 8; ++j) val = (lane == j) ? ga[j] : val;
	v_pk_add_f32 v[162:163], v[168:169], 1.0 op_sel_hi:[1,0]
	s_nop 0
	v_pk_fma_f32 v[162:163], v[228:229], v[162:163], v[164:165]
	v_pk_add_f32 v[168:169], v[170:171], 1.0 op_sel_hi:[1,0]
	v_fmac_f32_e32 v177, v96, v162
	v_fmac_f32_e32 v187, v97, v162
	v_fmac_f32_e32 v189, v98, v162
	v_fmac_f32_e32 v191, v99, v162
	v_fmac_f32_e32 v193, v100, v162
	v_fmac_f32_e32 v213, v101, v162
	v_fmac_f32_e32 v224, v102, v162
	v_fmac_f32_e32 v225, v103, v162
	v_pk_fma_f32 v[164:165], v[222:223], v[168:169], v[166:167]
	v_fmac_f32_e32 v177, v104, v163
	v_fmac_f32_e32 v187, v105, v163
	v_fmac_f32_e32 v189, v106, v163
	v_fmac_f32_e32 v191, v107, v163
	v_fmac_f32_e32 v193, v108, v163
	v_fmac_f32_e32 v213, v109, v163
	v_fmac_f32_e32 v224, v110, v163
	v_fmac_f32_e32 v225, v111, v163
	v_fmac_f32_e32 v177, v112, v164
	v_fmac_f32_e32 v187, v113, v164
	v_fmac_f32_e32 v189, v114, v164
	v_fmac_f32_e32 v191, v115, v164
	v_fmac_f32_e32 v193, v116, v164
	v_fmac_f32_e32 v213, v117, v164
	v_fmac_f32_e32 v224, v118, v164
	v_fmac_f32_e32 v225, v119, v164
	v_cvt_pk_bf16_f32 v166, v162, v163
	v_cvt_pk_bf16_f32 v167, v164, v165
	v_fmac_f32_e32 v177, v120, v165
	v_fmac_f32_e32 v187, v121, v165
	v_fmac_f32_e32 v189, v122, v165
	v_fmac_f32_e32 v191, v123, v165
	v_fmac_f32_e32 v193, v124, v165
	v_fmac_f32_e32 v213, v125, v165
	v_fmac_f32_e32 v224, v126, v165
	v_fmac_f32_e32 v225, v127, v165
	global_store_dwordx2 v[160:161], v[166:167], off offset:1536
	v_add_f32_dpp v160, v177, v177 quad_perm:[1,0,3,2] row_mask:0xf bank_mask:0xf bound_ctrl:1
	v_add_f32_dpp v161, v187, v187 quad_perm:[1,0,3,2] row_mask:0xf bank_mask:0xf bound_ctrl:1
	v_add_f32_dpp v162, v189, v189 quad_perm:[1,0,3,2] row_mask:0xf bank_mask:0xf bound_ctrl:1
	v_add_f32_dpp v163, v191, v191 quad_perm:[1,0,3,2] row_mask:0xf bank_mask:0xf bound_ctrl:1
	v_add_f32_dpp v164, v193, v193 quad_perm:[1,0,3,2] row_mask:0xf bank_mask:0xf bound_ctrl:1
	v_add_f32_dpp v165, v213, v213 quad_perm:[1,0,3,2] row_mask:0xf bank_mask:0xf bound_ctrl:1
	v_add_f32_dpp v166, v224, v224 quad_perm:[1,0,3,2] row_mask:0xf bank_mask:0xf bound_ctrl:1
	v_add_f32_dpp v167, v225, v225 quad_perm:[1,0,3,2] row_mask:0xf bank_mask:0xf bound_ctrl:1
	v_add_f32_dpp v160, v160, v160 quad_perm:[2,3,0,1] row_mask:0xf bank_mask:0xf bound_ctrl:1
	v_add_f32_dpp v161, v161, v161 quad_perm:[2,3,0,1] row_mask:0xf bank_mask:0xf bound_ctrl:1
	v_add_f32_dpp v162, v162, v162 quad_perm:[2,3,0,1] row_mask:0xf bank_mask:0xf bound_ctrl:1
	v_add_f32_dpp v163, v163, v163 quad_perm:[2,3,0,1] row_mask:0xf bank_mask:0xf bound_ctrl:1
	v_add_f32_dpp v164, v164, v164 quad_perm:[2,3,0,1] row_mask:0xf bank_mask:0xf bound_ctrl:1
	v_add_f32_dpp v165, v165, v165 quad_perm:[2,3,0,1] row_mask:0xf bank_mask:0xf bound_ctrl:1
	v_add_f32_dpp v166, v166, v166 quad_perm:[2,3,0,1] row_mask:0xf bank_mask:0xf bound_ctrl:1
	v_add_f32_dpp v167, v167, v167 quad_perm:[2,3,0,1] row_mask:0xf bank_mask:0xf bound_ctrl:1
	v_add_f32_dpp v160, v160, v160 row_half_mirror row_mask:0xf bank_mask:0xf bound_ctrl:1
	v_add_f32_dpp v161, v161, v161 row_half_mirror row_mask:0xf bank_mask:0xf bound_ctrl:1
	v_add_f32_dpp v162, v162, v162 row_half_mirror row_mask:0xf bank_mask:0xf bound_ctrl:1
	v_add_f32_dpp v163, v163, v163 row_half_mirror row_mask:0xf bank_mask:0xf bound_ctrl:1
	v_add_f32_dpp v164, v164, v164 row_half_mirror row_mask:0xf bank_mask:0xf bound_ctrl:1
	v_add_f32_dpp v165, v165, v165 row_half_mirror row_mask:0xf bank_mask:0xf bound_ctrl:1
	v_add_f32_dpp v166, v166, v166 row_half_mirror row_mask:0xf bank_mask:0xf bound_ctrl:1
	v_add_f32_dpp v167, v167, v167 row_half_mirror row_mask:0xf bank_mask:0xf bound_ctrl:1
	v_add_f32_dpp v160, v160, v160 row_mirror row_mask:0xf bank_mask:0xf bound_ctrl:1
	v_add_f32_dpp v161, v161, v161 row_mirror row_mask:0xf bank_mask:0xf bound_ctrl:1
	v_add_f32_dpp v162, v162, v162 row_mirror row_mask:0xf bank_mask:0xf bound_ctrl:1
	v_add_f32_dpp v163, v163, v163 row_mirror row_mask:0xf bank_mask:0xf bound_ctrl:1
	v_add_f32_dpp v164, v164, v164 row_mirror row_mask:0xf bank_mask:0xf bound_ctrl:1
	v_add_f32_dpp v165, v165, v165 row_mirror row_mask:0xf bank_mask:0xf bound_ctrl:1
	v_add_f32_dpp v166, v166, v166 row_mirror row_mask:0xf bank_mask:0xf bound_ctrl:1
	v_add_f32_dpp v167, v167, v167 row_mirror row_mask:0xf bank_mask:0xf bound_ctrl:1
	v_readlane_b32 s16, v160, 0
	v_readlane_b32 s31, v160, 16
	v_readlane_b32 s17, v160, 32
	v_readlane_b32 s30, v160, 48
	v_readlane_b32 s34, v161, 0
	v_readlane_b32 s42, v161, 16
	v_readlane_b32 s35, v161, 32
	v_readlane_b32 s41, v161, 48
	v_readlane_b32 s43, v162, 0
	v_readlane_b32 s46, v162, 16
	v_readlane_b32 s44, v162, 32
	v_readlane_b32 s45, v162, 48
	v_readlane_b32 s47, v163, 0
	v_readlane_b32 s50, v163, 16
	v_readlane_b32 s48, v163, 32
	v_readlane_b32 s49, v163, 48
	v_readlane_b32 s51, v164, 0
	v_readlane_b32 s55, v164, 16
	v_readlane_b32 s52, v164, 32
	v_readlane_b32 s53, v164, 48
	v_readlane_b32 s56, v165, 0
	v_readlane_b32 s73, v165, 16
	v_readlane_b32 s57, v165, 32
	v_readlane_b32 s72, v165, 48
	v_readlane_b32 s74, v166, 0
	v_readlane_b32 s83, v166, 16
	v_readlane_b32 s75, v166, 32
	v_readlane_b32 s82, v166, 48
	v_readlane_b32 s84, v167, 0
	v_readlane_b32 s87, v167, 16
	v_readlane_b32 s85, v167, 32
	v_readlane_b32 s86, v167, 48
	s_and_saveexec_b64 s[28:29], vcc
	s_cbranch_execz .LBB0_205
	v_mov_b32_e32 v166, s42
	v_mov_b32_e32 v167, s31
	v_mov_b32_e32 v165, s46
	v_add_f32_e32 v166, s34, v166
	v_add_f32_e32 v167, s16, v167
	v_mov_b32_e32 v164, s50
	v_add_f32_e32 v165, s43, v165
	v_add_f32_e32 v166, s35, v166
	v_add_f32_e32 v167, s17, v167
	v_mov_b32_e32 v163, s55
	v_add_f32_e32 v164, s47, v164
	v_add_f32_e32 v165, s44, v165
	v_add_f32_e32 v166, s41, v166
	v_add_f32_e32 v167, s30, v167
	v_mov_b32_e32 v162, s73
	v_add_f32_e32 v163, s51, v163
	v_add_f32_e32 v164, s48, v164
	v_add_f32_e32 v165, s45, v165
	v_cndmask_b32_e64 v166, v167, v166, s[0:1]
	v_mov_b32_e32 v161, s83
	v_add_f32_e32 v162, s56, v162
	v_add_f32_e32 v163, s52, v163
	v_add_f32_e32 v164, s49, v164
	v_cndmask_b32_e64 v165, v166, v165, s[14:15]
	v_mov_b32_e32 v160, s87
	v_add_f32_e32 v161, s74, v161
	v_add_f32_e32 v162, s57, v162
	v_add_f32_e32 v163, s53, v163
	v_cndmask_b32_e64 v164, v165, v164, s[4:5]
	v_add_f32_e32 v160, s84, v160
	v_add_f32_e32 v161, s75, v161
	v_add_f32_e32 v162, s72, v162
	v_cndmask_b32_e64 v163, v164, v163, s[6:7]
	v_add_f32_e32 v160, s85, v160
	v_add_f32_e32 v161, s82, v161
	v_cndmask_b32_e64 v162, v163, v162, s[8:9]
	v_add_f32_e32 v160, s86, v160
	v_cndmask_b32_e64 v161, v162, v161, s[10:11]
	v_cndmask_b32_e64 v160, v161, v160, s[12:13]
	ds_write_b32 v253, v160 offset:32
; DI uint2 pk4(f32x4 v) { return make_uint2(pk2(v[0], v[1]), pk2(v[2], v[3])); }
; DI void phase1(const Params& p, unsigned char* smem) {
;     ...
;         for (int rr = 0; rr < 4; ++rr) {
;             const int row = row0 + rr;
;             float mean, rstd; row_stats(vv[rr], mean, rstd);
;             const float* mb = mod + (row >> 13) * 6144;
;             float ga[8];
; #pragma unroll
;             for (int j = 0; j < 8; ++j) ga[j] = 0.f;
; #pragma unroll
;             for (int i = 0; i < 4; ++i) {
;                 int c = i * 256 + lane * 4;
;                 float4 sh = *(const float4*)(mb + c), sc = *(const float4*)(mb + 1024 + c);
;                 f32x4 o;
;                 o[0] = (vv[rr][4 * i] - mean) * rstd * (1.f + sc.x) + sh.x;
;                 o[1] = (vv[rr][4 * i + 1] - mean) * rstd * (1.f + sc.y) + sh.y;
;                 o[2] = (vv[rr][4 * i + 2] - mean) * rstd * (1.f + sc.z) + sh.z;
;                 o[3] = (vv[rr][4 * i + 3] - mean) * rstd * (1.f + sc.w) + sh.w;
;                 *(uint2*)(h1 + (size_t)row * 1024 + c) = pk4(o);
; #pragma unroll
;                 for (int e = 0; e < 4; ++e) {
;                     const float4 w0 = gw0[i * 4 + e], w1 = gw1[i * 4 + e];
;                     ga[0] += o[e] * w0.x; ga[1] += o[e] * w0.y; ga[2] += o[e] * w0.z; ga[3] += o[e] * w0.w;
;                     ga[4] += o[e] * w1.x; ga[5] += o[e] * w1.y; ga[6] += o[e] * w1.z; ga[7] += o[e] * w1.w;
;                 }
.LBB0_205:
	s_or_b64 exec, exec, s[28:29]
	ds_read_b128 v[160:163], v237 offset:5120
	ds_read_b128 v[164:167], v237 offset:1024
	v_add_f32_e32 v170, 0, v156
	v_add_f32_e32 v170, v170, v157
	v_add_f32_e32 v170, v170, v158
	v_add_f32_e32 v170, v170, v159
	v_add_f32_e32 v170, v170, v152
	v_add_f32_e32 v170, v170, v153
	v_add_f32_e32 v170, v170, v154
	v_add_f32_e32 v170, v170, v155
	v_add_f32_e32 v170, v170, v148
	v_add_f32_e32 v170, v170, v149
	v_add_f32_e32 v170, v170, v150
	v_add_f32_e32 v170, v170, v151
	v_add_f32_e32 v170, v170, v144
	v_add_f32_e32 v170, v170, v145
	v_add_f32_e32 v170, v170, v146
	v_add_f32_e32 v170, v170, v147
	v_lshlrev_b64 v[168:169], 11, v[202:203]
	s_nop 0
	v_add_f32_dpp v170, v170, v170 quad_perm:[1,0,3,2] row_mask:0xf bank_mask:0xf bound_ctrl:1
	s_nop 1
	v_add_f32_dpp v170, v170, v170 quad_perm:[2,3,0,1] row_mask:0xf bank_mask:0xf bound_ctrl:1
	s_nop 1
	v_add_f32_dpp v170, v170, v170 row_half_mirror row_mask:0xf bank_mask:0xf bound_ctrl:1
	s_nop 1
	v_add_f32_dpp v170, v170, v170 row_mirror row_mask:0xf bank_mask:0xf bound_ctrl:1
	s_nop 0
	v_readlane_b32 s17, v170, 16
	v_readlane_b32 s16, v170, 0
	v_readlane_b32 s18, v170, 32
	v_readlane_b32 s19, v170, 48
	v_mov_b32_e32 v170, s17
	v_add_f32_e32 v170, s16, v170
	v_add_f32_e32 v170, s18, v170
	v_add_f32_e32 v170, s19, v170
	v_mul_f32_e32 v170, 0x3a800000, v170
	v_pk_add_f32 v[156:157], v[156:157], v[170:171] op_sel_hi:[1,0] neg_lo:[0,1] neg_hi:[0,1]
	v_pk_add_f32 v[158:159], v[158:159], v[170:171] op_sel_hi:[1,0] neg_lo:[0,1] neg_hi:[0,1]
	v_pk_add_f32 v[214:215], v[148:149], v[170:171] op_sel_hi:[1,0] neg_lo:[0,1] neg_hi:[0,1]
	v_pk_add_f32 v[148:149], v[146:147], v[170:171] op_sel_hi:[1,0] neg_lo:[0,1] neg_hi:[0,1]
	v_pk_mul_f32 v[146:147], v[156:157], v[156:157]
	v_pk_add_f32 v[212:213], v[150:151], v[170:171] op_sel_hi:[1,0] neg_lo:[0,1] neg_hi:[0,1]
	v_pk_add_f32 v[150:151], v[144:145], v[170:171] op_sel_hi:[1,0] neg_lo:[0,1] neg_hi:[0,1]
	v_pk_mul_f32 v[144:145], v[158:159], v[158:159]
	v_add_f32_e32 v146, v146, v147
	v_pk_add_f32 v[174:175], v[152:153], v[170:171] op_sel_hi:[1,0] neg_lo:[0,1] neg_hi:[0,1]
	v_add_f32_e32 v144, v144, v146
	v_pk_add_f32 v[172:173], v[154:155], v[170:171] op_sel_hi:[1,0] neg_lo:[0,1] neg_hi:[0,1]
	v_pk_mul_f32 v[154:155], v[174:175], v[174:175]
	v_add_f32_e32 v144, v145, v144
	v_add_f32_e32 v144, v154, v144
	v_pk_mul_f32 v[152:153], v[172:173], v[172:173]
	v_add_f32_e32 v144, v155, v144
	v_add_f32_e32 v144, v152, v144
	v_pk_mul_f32 v[216:217], v[214:215], v[214:215]
	v_add_f32_e32 v144, v153, v144
	v_add_f32_e32 v144, v216, v144
	v_pk_mul_f32 v[170:171], v[212:213], v[212:213]
	v_add_f32_e32 v144, v217, v144
	v_add_f32_e32 v144, v170, v144
	v_pk_mul_f32 v[220:221], v[150:151], v[150:151]
	v_add_f32_e32 v144, v171, v144
	v_add_f32_e32 v144, v220, v144
	v_pk_mul_f32 v[218:219], v[148:149], v[148:149]
	v_add_f32_e32 v144, v221, v144
	v_add_f32_e32 v144, v218, v144
	v_add_f32_e32 v144, v219, v144
	s_waitcnt lgkmcnt(1)
	v_pk_add_f32 v[154:155], v[162:163], 1.0 op_sel_hi:[1,0]
	v_add_f32_dpp v144, v144, v144 quad_perm:[1,0,3,2] row_mask:0xf bank_mask:0xf bound_ctrl:1
	v_pk_add_f32 v[146:147], v[160:161], 1.0 op_sel_hi:[1,0]
	s_nop 0
	v_add_f32_dpp v144, v144, v144 quad_perm:[2,3,0,1] row_mask:0xf bank_mask:0xf bound_ctrl:1
	s_nop 1
	v_add_f32_dpp v144, v144, v144 row_half_mirror row_mask:0xf bank_mask:0xf bound_ctrl:1
	s_nop 1
	v_add_f32_dpp v144, v144, v144 row_mirror row_mask:0xf bank_mask:0xf bound_ctrl:1
	s_nop 0
	v_readlane_b32 s17, v144, 16
	v_readlane_b32 s16, v144, 0
	v_readlane_b32 s18, v144, 32
	v_readlane_b32 s19, v144, 48
	v_mov_b32_e32 v144, s17
	v_add_f32_e32 v144, s16, v144
	v_add_f32_e32 v144, s18, v144
	v_add_f32_e32 v144, s19, v144
	v_fmamk_f32 v144, v144, 0x3a800000, v232
	v_mul_f32_e32 v145, 0x4b800000, v144
	v_cmp_gt_f32_e64 s[16:17], s36, v144
	s_nop 1
	v_cndmask_b32_e64 v144, v144, v145, s[16:17]
	v_rsq_f32_e32 v152, v144
	v_lshl_add_u64 v[144:145], v[184:185], 0, v[168:169]
	v_mul_f32_e32 v153, 0x45800000, v152
	v_cndmask_b32_e64 v162, v152, v153, s[16:17]
	v_pk_mul_f32 v[152:153], v[156:157], v[162:163] op_sel_hi:[1,0]
	v_pk_mul_f32 v[168:169], v[214:215], v[162:163] op_sel_hi:[1,0]
	s_waitcnt lgkmcnt(0)
	v_pk_fma_f32 v[152:153], v[146:147], v[152:153], v[164:165]
	v_pk_mul_f32 v[146:147], v[158:159], v[162:163] op_sel_hi:[1,0]
	v_pk_mul_f32 v[164:165], v[174:175], v[162:163] op_sel_hi:[1,0]
	v_pk_fma_f32 v[146:147], v[154:155], v[146:147], v[166:167]
	v_cvt_pk_bf16_f32 v154, v152, v153
	v_cvt_pk_bf16_f32 v155, v146, v147
	global_store_dwordx2 v[144:145], v[154:155], off
	ds_read_b128 v[154:157], v237 offset:6144
	s_nop 0
	ds_read_b128 v[158:161], v237 offset:2048
	v_pk_mul_f32 v[166:167], v[172:173], v[162:163] op_sel_hi:[1,0]
	v_pk_mul_f32 v[170:171], v[212:213], v[162:163] op_sel_hi:[1,0]
	v_pk_mul_f32 v[172:173], v[150:151], v[162:163] op_sel_hi:[1,0]
	v_pk_mul_f32 v[162:163], v[148:149], v[162:163] op_sel_hi:[1,0]
	v_fma_f32 v174, v0, v152, 0
	v_fma_f32 v175, v1, v152, 0
	v_fma_f32 v177, v2, v152, 0
	v_fma_f32 v187, v3, v152, 0
	v_fma_f32 v189, v4, v152, 0
	v_fma_f32 v191, v5, v152, 0
	v_fma_f32 v193, v6, v152, 0
	v_fma_f32 v203, v7, v152, 0
	v_fmac_f32_e32 v174, v8, v153
	v_fmac_f32_e32 v175, v9, v153
	v_fmac_f32_e32 v177, v10, v153
	v_fmac_f32_e32 v187, v11, v153
	v_fmac_f32_e32 v189, v12, v153
	v_fmac_f32_e32 v191, v13, v153
	v_fmac_f32_e32 v193, v14, v153
	v_fmac_f32_e32 v203, v15, v153
	v_fmac_f32_e32 v174, v16, v146
	v_fmac_f32_e32 v175, v17, v146
	v_fmac_f32_e32 v177, v18, v146
	v_fmac_f32_e32 v187, v19, v146
	v_fmac_f32_e32 v189, v20, v146
	v_fmac_f32_e32 v191, v21, v146
	v_fmac_f32_e32 v193, v22, v146
	v_fmac_f32_e32 v203, v23, v146
	v_fmac_f32_e32 v174, v24, v147
	v_fmac_f32_e32 v175, v25, v147
	v_fmac_f32_e32 v177, v26, v147
	v_fmac_f32_e32 v187, v27, v147
	v_fmac_f32_e32 v189, v28, v147
	v_fmac_f32_e32 v191, v29, v147
	v_fmac_f32_e32 v193, v30, v147
	v_fmac_f32_e32 v203, v31, v147
	s_waitcnt lgkmcnt(1)
; DI uint2 pk4(f32x4 v) { return make_uint2(pk2(v[0], v[1]), pk2(v[2], v[3])); }
; DI void phase1(const Params& p, unsigned char* smem) {
;     ...
;             for (int i = 0; i < 4; ++i) {
;                 int c = i * 256 + lane * 4;
;                 float4 sh = *(const float4*)(mb + c), sc = *(const float4*)(mb + 1024 + c);
;                 f32x4 o;
;                 o[0] = (vv[rr][4 * i] - mean) * rstd * (1.f + sc.x) + sh.x;
;                 o[1] = (vv[rr][4 * i + 1] - mean) * rstd * (1.f + sc.y) + sh.y;
;                 o[2] = (vv[rr][4 * i + 2] - mean) * rstd * (1.f + sc.z) + sh.z;
;                 o[3] = (vv[rr][4 * i + 3] - mean) * rstd * (1.f + sc.w) + sh.w;
;                 *(uint2*)(h1 + (size_t)row * 1024 + c) = pk4(o);
; #pragma unroll
;                 for (int e = 0; e < 4; ++e) {
;                     const float4 w0 = gw0[i * 4 + e], w1 = gw1[i * 4 + e];
;                     ga[0] += o[e] * w0.x; ga[1] += o[e] * w0.y; ga[2] += o[e] * w0.z; ga[3] += o[e] * w0.w;
;                     ga[4] += o[e] * w1.x; ga[5] += o[e] * w1.y; ga[6] += o[e] * w1.z; ga[7] += o[e] * w1.w;
;                 }
;             }
; #pragma unroll
;             for (int j = 0; j < 8; ++j) ga[j] = wsum(ga[j]);
	v_pk_add_f32 v[154:155], v[154:155], 1.0 op_sel_hi:[1,0]
	v_pk_add_f32 v[156:157], v[156:157], 1.0 op_sel_hi:[1,0]
	s_waitcnt lgkmcnt(0)
	v_pk_fma_f32 v[164:165], v[164:165], v[154:155], v[158:159]
	v_pk_fma_f32 v[166:167], v[166:167], v[156:157], v[160:161]
	v_cvt_pk_bf16_f32 v154, v164, v165
	v_cvt_pk_bf16_f32 v155, v166, v167
	global_store_dwordx2 v[144:145], v[154:155], off offset:512
	ds_read_b128 v[154:157], v237 offset:7168
	s_nop 0
	ds_read_b128 v[158:161], v237 offset:3072
	v_fmac_f32_e32 v174, v32, v164
	v_fmac_f32_e32 v175, v33, v164
	v_fmac_f32_e32 v177, v34, v164
	v_fmac_f32_e32 v187, v35, v164
	v_fmac_f32_e32 v189, v36, v164
	v_fmac_f32_e32 v191, v37, v164
	v_fmac_f32_e32 v193, v38, v164
	v_fmac_f32_e32 v203, v39, v164
	v_fmac_f32_e32 v174, v40, v165
	v_fmac_f32_e32 v175, v41, v165
	v_fmac_f32_e32 v177, v42, v165
	v_fmac_f32_e32 v187, v43, v165
	v_fmac_f32_e32 v189, v44, v165
	v_fmac_f32_e32 v191, v45, v165
	v_fmac_f32_e32 v193, v46, v165
	v_fmac_f32_e32 v203, v47, v165
	v_fmac_f32_e32 v174, v48, v166
	v_fmac_f32_e32 v175, v49, v166
	v_fmac_f32_e32 v177, v50, v166
	v_fmac_f32_e32 v187, v51, v166
	v_fmac_f32_e32 v189, v52, v166
	v_fmac_f32_e32 v191, v53, v166
	v_fmac_f32_e32 v193, v54, v166
	v_fmac_f32_e32 v203, v55, v166
	v_fmac_f32_e32 v174, v56, v167
	v_fmac_f32_e32 v175, v57, v167
	v_fmac_f32_e32 v177, v58, v167
	v_fmac_f32_e32 v187, v59, v167
	v_fmac_f32_e32 v189, v60, v167
	v_fmac_f32_e32 v191, v61, v167
	v_fmac_f32_e32 v193, v62, v167
	v_fmac_f32_e32 v203, v63, v167
	s_waitcnt lgkmcnt(1)
	v_pk_add_f32 v[148:149], v[154:155], 1.0 op_sel_hi:[1,0]
	v_pk_add_f32 v[150:151], v[156:157], 1.0 op_sel_hi:[1,0]
	s_waitcnt lgkmcnt(0)
	v_pk_fma_f32 v[156:157], v[168:169], v[148:149], v[158:159]
	v_pk_fma_f32 v[158:159], v[170:171], v[150:151], v[160:161]
	v_cvt_pk_bf16_f32 v148, v156, v157
	v_cvt_pk_bf16_f32 v149, v158, v159
	global_store_dwordx2 v[144:145], v[148:149], off offset:1024
	ds_read_b128 v[148:151], v237 offset:4096
	s_nop 0
	ds_read_b128 v[152:155], v237 offset:8192
	v_fmac_f32_e32 v174, v64, v156
	v_fmac_f32_e32 v175, v65, v156
	v_fmac_f32_e32 v177, v66, v156
	v_fmac_f32_e32 v187, v67, v156
	v_fmac_f32_e32 v189, v68, v156
	v_fmac_f32_e32 v191, v69, v156
	v_fmac_f32_e32 v193, v70, v156
	v_fmac_f32_e32 v203, v71, v156
	v_fmac_f32_e32 v174, v72, v157
	v_fmac_f32_e32 v175, v73, v157
	v_fmac_f32_e32 v177, v74, v157
	v_fmac_f32_e32 v187, v75, v157
	v_fmac_f32_e32 v189, v76, v157
	v_fmac_f32_e32 v191, v77, v157
	v_fmac_f32_e32 v193, v78, v157
	v_fmac_f32_e32 v203, v79, v157
	v_fmac_f32_e32 v174, v80, v158
	v_fmac_f32_e32 v175, v81, v158
	v_fmac_f32_e32 v177, v82, v158
	v_fmac_f32_e32 v187, v83, v158
	v_fmac_f32_e32 v189, v84, v158
	v_fmac_f32_e32 v191, v85, v158
	v_fmac_f32_e32 v193, v86, v158
	v_fmac_f32_e32 v203, v87, v158
	v_fmac_f32_e32 v174, v88, v159
	v_fmac_f32_e32 v175, v89, v159
	v_fmac_f32_e32 v177, v90, v159
	v_fmac_f32_e32 v187, v91, v159
	v_fmac_f32_e32 v189, v92, v159
	v_fmac_f32_e32 v191, v93, v159
	v_fmac_f32_e32 v193, v94, v159
	v_fmac_f32_e32 v203, v95, v159
	s_waitcnt lgkmcnt(0)
	v_pk_add_f32 v[146:147], v[152:153], 1.0 op_sel_hi:[1,0]
	s_nop 0
	v_pk_fma_f32 v[146:147], v[172:173], v[146:147], v[148:149]
	v_pk_add_f32 v[152:153], v[154:155], 1.0 op_sel_hi:[1,0]
	v_fmac_f32_e32 v174, v96, v146
	v_fmac_f32_e32 v175, v97, v146
	v_fmac_f32_e32 v177, v98, v146
	v_fmac_f32_e32 v187, v99, v146
	v_fmac_f32_e32 v189, v100, v146
	v_fmac_f32_e32 v191, v101, v146
	v_fmac_f32_e32 v193, v102, v146
	v_fmac_f32_e32 v203, v103, v146
	v_pk_fma_f32 v[148:149], v[162:163], v[152:153], v[150:151]
	v_fmac_f32_e32 v174, v104, v147
	v_fmac_f32_e32 v175, v105, v147
	v_fmac_f32_e32 v177, v106, v147
	v_fmac_f32_e32 v187, v107, v147
	v_fmac_f32_e32 v189, v108, v147
	v_fmac_f32_e32 v191, v109, v147
	v_fmac_f32_e32 v193, v110, v147
	v_fmac_f32_e32 v203, v111, v147
	v_fmac_f32_e32 v174, v112, v148
	v_fmac_f32_e32 v175, v113, v148
	v_fmac_f32_e32 v177, v114, v148
	v_fmac_f32_e32 v187, v115, v148
	v_fmac_f32_e32 v189, v116, v148
	v_fmac_f32_e32 v191, v117, v148
	v_fmac_f32_e32 v193, v118, v148
	v_fmac_f32_e32 v203, v119, v148
	v_cvt_pk_bf16_f32 v150, v146, v147
	v_cvt_pk_bf16_f32 v151, v148, v149
	v_fmac_f32_e32 v174, v120, v149
	v_fmac_f32_e32 v175, v121, v149
	v_fmac_f32_e32 v177, v122, v149
	v_fmac_f32_e32 v187, v123, v149
	v_fmac_f32_e32 v189, v124, v149
	v_fmac_f32_e32 v191, v125, v149
	v_fmac_f32_e32 v193, v126, v149
	v_fmac_f32_e32 v203, v127, v149
	global_store_dwordx2 v[144:145], v[150:151], off offset:1536
	v_add_f32_dpp v144, v174, v174 quad_perm:[1,0,3,2] row_mask:0xf bank_mask:0xf bound_ctrl:1
	v_add_f32_dpp v145, v175, v175 quad_perm:[1,0,3,2] row_mask:0xf bank_mask:0xf bound_ctrl:1
	v_add_f32_dpp v146, v177, v177 quad_perm:[1,0,3,2] row_mask:0xf bank_mask:0xf bound_ctrl:1
	v_add_f32_dpp v147, v187, v187 quad_perm:[1,0,3,2] row_mask:0xf bank_mask:0xf bound_ctrl:1
	v_add_f32_dpp v148, v189, v189 quad_perm:[1,0,3,2] row_mask:0xf bank_mask:0xf bound_ctrl:1
	v_add_f32_dpp v149, v191, v191 quad_perm:[1,0,3,2] row_mask:0xf bank_mask:0xf bound_ctrl:1
	v_add_f32_dpp v150, v193, v193 quad_perm:[1,0,3,2] row_mask:0xf bank_mask:0xf bound_ctrl:1
	v_add_f32_dpp v151, v203, v203 quad_perm:[1,0,3,2] row_mask:0xf bank_mask:0xf bound_ctrl:1
	v_add_f32_dpp v144, v144, v144 quad_perm:[2,3,0,1] row_mask:0xf bank_mask:0xf bound_ctrl:1
	v_add_f32_dpp v145, v145, v145 quad_perm:[2,3,0,1] row_mask:0xf bank_mask:0xf bound_ctrl:1
	v_add_f32_dpp v146, v146, v146 quad_perm:[2,3,0,1] row_mask:0xf bank_mask:0xf bound_ctrl:1
	v_add_f32_dpp v147, v147, v147 quad_perm:[2,3,0,1] row_mask:0xf bank_mask:0xf bound_ctrl:1
; DI float logsig(float x) { return (x < 0.f) ? (x - log1pf(__expf(x))) : (-log1pf(__expf(-x))); }
; DI void row_stats(const float (&v)[16], float& mean, float& rstd) {
;     float s = 0.f;
; #pragma unroll
;     for (int i = 0; i < 16; ++i) s += v[i];
;     mean = wsum(s) * (1.f / 1024.f);
;     float q = 0.f;
; #pragma unroll
;     for (int i = 0; i < 16; ++i) { float d = v[i] - mean; q += d * d; }
;     rstd = rsqrtf(wsum(q) * (1.f / 1024.f) + 1e-5f);
; }
; DI void phase1(const Params& p, unsigned char* smem) {
;     ...
; #pragma unroll
;             for (int j = 0; j < 8; ++j) ga[j] = wsum(ga[j]);
;             if (lane < 8) {
;                 float val = ga[0];
; #pragma unroll
;                 for (int j = 1; j < 8; ++j) val = (lane == j) ? ga[j] : val;
;                 val += p.in[5][2048 + lane];
;                 const int b = row >> 13, sidx = row & 8191;
;                 if (lane < 4) ig[(size_t)(b * 4 + lane) * 8192 + sidx] = val;
;                 else lf[(size_t)(b * 4 + lane - 4) * 8192 + sidx] = logsig(val);
;             }
	v_add_f32_dpp v148, v148, v148 quad_perm:[2,3,0,1] row_mask:0xf bank_mask:0xf bound_ctrl:1
	v_add_f32_dpp v149, v149, v149 quad_perm:[2,3,0,1] row_mask:0xf bank_mask:0xf bound_ctrl:1
	v_add_f32_dpp v150, v150, v150 quad_perm:[2,3,0,1] row_mask:0xf bank_mask:0xf bound_ctrl:1
	v_add_f32_dpp v151, v151, v151 quad_perm:[2,3,0,1] row_mask:0xf bank_mask:0xf bound_ctrl:1
	v_add_f32_dpp v144, v144, v144 row_half_mirror row_mask:0xf bank_mask:0xf bound_ctrl:1
	v_add_f32_dpp v145, v145, v145 row_half_mirror row_mask:0xf bank_mask:0xf bound_ctrl:1
	v_add_f32_dpp v146, v146, v146 row_half_mirror row_mask:0xf bank_mask:0xf bound_ctrl:1
	v_add_f32_dpp v147, v147, v147 row_half_mirror row_mask:0xf bank_mask:0xf bound_ctrl:1
	v_add_f32_dpp v148, v148, v148 row_half_mirror row_mask:0xf bank_mask:0xf bound_ctrl:1
	v_add_f32_dpp v149, v149, v149 row_half_mirror row_mask:0xf bank_mask:0xf bound_ctrl:1
	v_add_f32_dpp v150, v150, v150 row_half_mirror row_mask:0xf bank_mask:0xf bound_ctrl:1
	v_add_f32_dpp v151, v151, v151 row_half_mirror row_mask:0xf bank_mask:0xf bound_ctrl:1
	v_add_f32_dpp v144, v144, v144 row_mirror row_mask:0xf bank_mask:0xf bound_ctrl:1
	v_add_f32_dpp v145, v145, v145 row_mirror row_mask:0xf bank_mask:0xf bound_ctrl:1
	v_add_f32_dpp v146, v146, v146 row_mirror row_mask:0xf bank_mask:0xf bound_ctrl:1
	v_add_f32_dpp v147, v147, v147 row_mirror row_mask:0xf bank_mask:0xf bound_ctrl:1
	v_add_f32_dpp v148, v148, v148 row_mirror row_mask:0xf bank_mask:0xf bound_ctrl:1
	v_add_f32_dpp v149, v149, v149 row_mirror row_mask:0xf bank_mask:0xf bound_ctrl:1
	v_add_f32_dpp v150, v150, v150 row_mirror row_mask:0xf bank_mask:0xf bound_ctrl:1
	v_add_f32_dpp v151, v151, v151 row_mirror row_mask:0xf bank_mask:0xf bound_ctrl:1
	v_readlane_b32 s16, v144, 0
	v_readlane_b32 s31, v144, 16
	v_readlane_b32 s17, v144, 32
	v_readlane_b32 s30, v144, 48
	v_readlane_b32 s34, v145, 0
	v_readlane_b32 s42, v145, 16
	v_readlane_b32 s35, v145, 32
	v_readlane_b32 s41, v145, 48
	v_readlane_b32 s43, v146, 0
	v_readlane_b32 s46, v146, 16
	v_readlane_b32 s44, v146, 32
	v_readlane_b32 s45, v146, 48
	v_readlane_b32 s47, v147, 0
	v_readlane_b32 s50, v147, 16
	v_readlane_b32 s48, v147, 32
	v_readlane_b32 s49, v147, 48
	v_readlane_b32 s51, v148, 0
	v_readlane_b32 s55, v148, 16
	v_readlane_b32 s52, v148, 32
	v_readlane_b32 s53, v148, 48
	v_readlane_b32 s56, v149, 0
	v_readlane_b32 s73, v149, 16
	v_readlane_b32 s57, v149, 32
	v_readlane_b32 s72, v149, 48
	v_readlane_b32 s74, v150, 0
	v_readlane_b32 s83, v150, 16
	v_readlane_b32 s75, v150, 32
	v_readlane_b32 s82, v150, 48
	v_readlane_b32 s84, v151, 0
	v_readlane_b32 s87, v151, 16
	v_readlane_b32 s85, v151, 32
	v_readlane_b32 s86, v151, 48
	s_and_saveexec_b64 s[28:29], vcc
	s_cbranch_execz .LBB0_213
	v_mov_b32_e32 v150, s42
	v_mov_b32_e32 v151, s31
	v_mov_b32_e32 v149, s46
	v_add_f32_e32 v150, s34, v150
	v_add_f32_e32 v151, s16, v151
	v_mov_b32_e32 v148, s50
	v_add_f32_e32 v149, s43, v149
	v_add_f32_e32 v150, s35, v150
	v_add_f32_e32 v151, s17, v151
	v_mov_b32_e32 v147, s55
	v_add_f32_e32 v148, s47, v148
	v_add_f32_e32 v149, s44, v149
	v_add_f32_e32 v150, s41, v150
	v_add_f32_e32 v151, s30, v151
	v_mov_b32_e32 v146, s73
	v_add_f32_e32 v147, s51, v147
	v_add_f32_e32 v148, s48, v148
	v_add_f32_e32 v149, s45, v149
	v_cndmask_b32_e64 v150, v151, v150, s[0:1]
	v_mov_b32_e32 v145, s83
	v_add_f32_e32 v146, s56, v146
	v_add_f32_e32 v147, s52, v147
	v_add_f32_e32 v148, s49, v148
	v_cndmask_b32_e64 v149, v150, v149, s[14:15]
	v_mov_b32_e32 v144, s87
	v_add_f32_e32 v145, s74, v145
	v_add_f32_e32 v146, s57, v146
	v_add_f32_e32 v147, s53, v147
	v_cndmask_b32_e64 v148, v149, v148, s[4:5]
	v_add_f32_e32 v144, s84, v144
	v_add_f32_e32 v145, s75, v145
	v_add_f32_e32 v146, s72, v146
	v_cndmask_b32_e64 v147, v148, v147, s[6:7]
	v_add_f32_e32 v144, s85, v144
	v_add_f32_e32 v145, s82, v145
	v_cndmask_b32_e64 v146, v147, v146, s[8:9]
	v_add_f32_e32 v144, s86, v144
	v_cndmask_b32_e64 v145, v146, v145, s[10:11]
	v_cndmask_b32_e64 v144, v145, v144, s[12:13]
	ds_write_b32 v253, v144 offset:64
.LBB0_213:
	s_or_b64 exec, exec, s[28:29]
	ds_read_b128 v[144:147], v237 offset:5120
	ds_read_b128 v[148:151], v237 offset:1024
	v_add_f32_e32 v154, 0, v140
	v_add_f32_e32 v154, v154, v141
	v_add_f32_e32 v154, v154, v142
	v_add_f32_e32 v154, v154, v143
	v_add_f32_e32 v154, v154, v136
	v_add_f32_e32 v154, v154, v137
	v_add_f32_e32 v154, v154, v138
	v_add_f32_e32 v154, v154, v139
	v_add_f32_e32 v154, v154, v132
	v_add_f32_e32 v154, v154, v133
	v_add_f32_e32 v154, v154, v134
	v_add_f32_e32 v154, v154, v135
	v_add_f32_e32 v154, v154, v128
	v_add_f32_e32 v154, v154, v129
	v_add_f32_e32 v154, v154, v130
	v_add_f32_e32 v154, v154, v131
	v_lshlrev_b64 v[152:153], 11, v[194:195]
	s_nop 0
	v_add_f32_dpp v154, v154, v154 quad_perm:[1,0,3,2] row_mask:0xf bank_mask:0xf bound_ctrl:1
	s_nop 1
	v_add_f32_dpp v154, v154, v154 quad_perm:[2,3,0,1] row_mask:0xf bank_mask:0xf bound_ctrl:1
	s_nop 1
	v_add_f32_dpp v154, v154, v154 row_half_mirror row_mask:0xf bank_mask:0xf bound_ctrl:1
	s_nop 1
	v_add_f32_dpp v154, v154, v154 row_mirror row_mask:0xf bank_mask:0xf bound_ctrl:1
	s_nop 0
	v_readlane_b32 s17, v154, 16
	v_readlane_b32 s16, v154, 0
	v_readlane_b32 s18, v154, 32
	v_readlane_b32 s19, v154, 48
	v_mov_b32_e32 v154, s17
	v_add_f32_e32 v154, s16, v154
	v_add_f32_e32 v154, s18, v154
	v_add_f32_e32 v154, s19, v154
	v_mul_f32_e32 v154, 0x3a800000, v154
	v_pk_add_f32 v[140:141], v[140:141], v[154:155] op_sel_hi:[1,0] neg_lo:[0,1] neg_hi:[0,1]
	v_pk_add_f32 v[142:143], v[142:143], v[154:155] op_sel_hi:[1,0] neg_lo:[0,1] neg_hi:[0,1]
	v_pk_add_f32 v[162:163], v[132:133], v[154:155] op_sel_hi:[1,0] neg_lo:[0,1] neg_hi:[0,1]
	v_pk_add_f32 v[132:133], v[130:131], v[154:155] op_sel_hi:[1,0] neg_lo:[0,1] neg_hi:[0,1]
	v_pk_mul_f32 v[130:131], v[140:141], v[140:141]
	v_pk_add_f32 v[160:161], v[134:135], v[154:155] op_sel_hi:[1,0] neg_lo:[0,1] neg_hi:[0,1]
	v_pk_add_f32 v[134:135], v[128:129], v[154:155] op_sel_hi:[1,0] neg_lo:[0,1] neg_hi:[0,1]
	v_pk_mul_f32 v[128:129], v[142:143], v[142:143]
	v_add_f32_e32 v130, v130, v131
	v_pk_add_f32 v[158:159], v[136:137], v[154:155] op_sel_hi:[1,0] neg_lo:[0,1] neg_hi:[0,1]
	v_add_f32_e32 v128, v128, v130
	v_pk_add_f32 v[156:157], v[138:139], v[154:155] op_sel_hi:[1,0] neg_lo:[0,1] neg_hi:[0,1]
	v_pk_mul_f32 v[138:139], v[158:159], v[158:159]
	v_add_f32_e32 v128, v129, v128
	v_add_f32_e32 v128, v138, v128
	v_pk_mul_f32 v[136:137], v[156:157], v[156:157]
	v_add_f32_e32 v128, v139, v128
	v_add_f32_e32 v128, v136, v128
	v_pk_mul_f32 v[164:165], v[162:163], v[162:163]
	v_add_f32_e32 v128, v137, v128
	v_add_f32_e32 v128, v164, v128
	v_pk_mul_f32 v[154:155], v[160:161], v[160:161]
	v_add_f32_e32 v128, v165, v128
	v_add_f32_e32 v128, v154, v128
	v_pk_mul_f32 v[168:169], v[134:135], v[134:135]
	v_add_f32_e32 v128, v155, v128
	v_add_f32_e32 v128, v168, v128
	v_pk_mul_f32 v[166:167], v[132:133], v[132:133]
	v_add_f32_e32 v128, v169, v128
	v_add_f32_e32 v128, v166, v128
	v_add_f32_e32 v128, v167, v128
	s_waitcnt lgkmcnt(1)
; DI void row_stats(const float (&v)[16], float& mean, float& rstd) {
;     ...
;     for (int i = 0; i < 16; ++i) { float d = v[i] - mean; q += d * d; }
;     rstd = rsqrtf(wsum(q) * (1.f / 1024.f) + 1e-5f);
; }
; DI void phase1(const Params& p, unsigned char* smem) {
;     unsigned char* ws = p.ws;
;     int ft_ = threadIdx.x; asm volatile("" : "+v"(ft_));
;     const int lane = ft_ & 63, wid = ft_ >> 6;
;     const float* mod = (const float*)(ws + OFF_MOD);
;     bf16_t* h1 = (bf16_t*)(ws + 1 * U_);
;     float4 gw0[16], gw1[16];
; #pragma unroll
;     for (int i = 0; i < 4; ++i)
; #pragma unroll
;         for (int e = 0; e < 4; ++e) {
;             const float* wp = p.in[4] + (size_t)(i * 256 + lane * 4 + e) * 4616 + 2048;
;             gw0[i * 4 + e] = *(const float4*)wp; gw1[i * 4 + e] = *(const float4*)(wp + 4);
;         }
;     float* ig = (float*)(ws + OFF_IG);
;     float* lf = (float*)(ws + OFF_LOGF);
;     for (int row0 = (blockIdx.x * 8 + wid) * 4; row0 < T_; row0 += gridDim.x * 32) {
;         float vv[4][16];
; #pragma unroll
;         for (int rr = 0; rr < 4; ++rr)
; #pragma unroll
;             for (int i = 0; i < 4; ++i) { float4 t = *(const float4*)(p.in[0] + (size_t)(row0 + rr) * 1024 + i * 256 + lane * 4); vv[rr][4 * i] = t.x; vv[rr][4 * i + 1] = t.y; vv[rr][4 * i + 2] = t.z; vv[rr][4 * i + 3] = t.w; }
; #pragma unroll
;         for (int rr = 0; rr < 4; ++rr) {
;             const int row = row0 + rr;
;             float mean, rstd; row_stats(vv[rr], mean, rstd);
;             const float* mb = mod + (row >> 13) * 6144;
;             float ga[8];
; #pragma unroll
;             for (int j = 0; j < 8; ++j) ga[j] = 0.f;
; #pragma unroll
;             for (int i = 0; i < 4; ++i) {
;                 int c = i * 256 + lane * 4;
;                 float4 sh = *(const float4*)(mb + c), sc = *(const float4*)(mb + 1024 + c);
;                 f32x4 o;
;                 o[0] = (vv[rr][4 * i] - mean) * rstd * (1.f + sc.x) + sh.x;
;                 o[1] = (vv[rr][4 * i + 1] - mean) * rstd * (1.f + sc.y) + sh.y;
;                 o[2] = (vv[rr][4 * i + 2] - mean) * rstd * (1.f + sc.z) + sh.z;
;                 o[3] = (vv[rr][4 * i + 3] - mean) * rstd * (1.f + sc.w) + sh.w;
;                 *(uint2*)(h1 + (size_t)row * 1024 + c) = pk4(o);
; #pragma unroll
;                 for (int e = 0; e < 4; ++e) {
	v_pk_add_f32 v[138:139], v[146:147], 1.0 op_sel_hi:[1,0]
	v_add_f32_dpp v128, v128, v128 quad_perm:[1,0,3,2] row_mask:0xf bank_mask:0xf bound_ctrl:1
	v_pk_add_f32 v[130:131], v[144:145], 1.0 op_sel_hi:[1,0]
	s_nop 0
	v_add_f32_dpp v128, v128, v128 quad_perm:[2,3,0,1] row_mask:0xf bank_mask:0xf bound_ctrl:1
	s_nop 1
	v_add_f32_dpp v128, v128, v128 row_half_mirror row_mask:0xf bank_mask:0xf bound_ctrl:1
	s_nop 1
	v_add_f32_dpp v128, v128, v128 row_mirror row_mask:0xf bank_mask:0xf bound_ctrl:1
	s_nop 0
	v_readlane_b32 s17, v128, 16
	v_readlane_b32 s16, v128, 0
	v_readlane_b32 s18, v128, 32
	v_readlane_b32 s19, v128, 48
	v_mov_b32_e32 v128, s17
	v_add_f32_e32 v128, s16, v128
	v_add_f32_e32 v128, s18, v128
	v_add_f32_e32 v128, s19, v128
	v_fmamk_f32 v128, v128, 0x3a800000, v232
	v_mul_f32_e32 v129, 0x4b800000, v128
	v_cmp_gt_f32_e64 s[16:17], s36, v128
	s_nop 1
	v_cndmask_b32_e64 v128, v128, v129, s[16:17]
	v_rsq_f32_e32 v136, v128
	v_lshl_add_u64 v[128:129], v[184:185], 0, v[152:153]
	v_mul_f32_e32 v137, 0x45800000, v136
	v_cndmask_b32_e64 v146, v136, v137, s[16:17]
	v_pk_mul_f32 v[136:137], v[140:141], v[146:147] op_sel_hi:[1,0]
	v_pk_mul_f32 v[152:153], v[162:163], v[146:147] op_sel_hi:[1,0]
	s_waitcnt lgkmcnt(0)
	v_pk_fma_f32 v[136:137], v[130:131], v[136:137], v[148:149]
	v_pk_mul_f32 v[130:131], v[142:143], v[146:147] op_sel_hi:[1,0]
	v_pk_mul_f32 v[148:149], v[158:159], v[146:147] op_sel_hi:[1,0]
	v_pk_fma_f32 v[130:131], v[138:139], v[130:131], v[150:151]
	v_cvt_pk_bf16_f32 v138, v136, v137
	v_cvt_pk_bf16_f32 v139, v130, v131
	global_store_dwordx2 v[128:129], v[138:139], off
	ds_read_b128 v[138:141], v237 offset:6144
	s_nop 0
	ds_read_b128 v[142:145], v237 offset:2048
	v_pk_mul_f32 v[150:151], v[156:157], v[146:147] op_sel_hi:[1,0]
	v_pk_mul_f32 v[154:155], v[160:161], v[146:147] op_sel_hi:[1,0]
	v_pk_mul_f32 v[156:157], v[134:135], v[146:147] op_sel_hi:[1,0]
	v_pk_mul_f32 v[146:147], v[132:133], v[146:147] op_sel_hi:[1,0]
	v_fma_f32 v158, v0, v136, 0
	v_fma_f32 v159, v1, v136, 0
	v_fma_f32 v160, v2, v136, 0
	v_fma_f32 v161, v3, v136, 0
	v_fma_f32 v162, v4, v136, 0
	v_fma_f32 v163, v5, v136, 0
	v_fma_f32 v164, v6, v136, 0
	v_fma_f32 v165, v7, v136, 0
	v_fmac_f32_e32 v158, v8, v137
	v_fmac_f32_e32 v159, v9, v137
	v_fmac_f32_e32 v160, v10, v137
	v_fmac_f32_e32 v161, v11, v137
	v_fmac_f32_e32 v162, v12, v137
	v_fmac_f32_e32 v163, v13, v137
	v_fmac_f32_e32 v164, v14, v137
	v_fmac_f32_e32 v165, v15, v137
	v_fmac_f32_e32 v158, v16, v130
	v_fmac_f32_e32 v159, v17, v130
	v_fmac_f32_e32 v160, v18, v130
	v_fmac_f32_e32 v161, v19, v130
	v_fmac_f32_e32 v162, v20, v130
	v_fmac_f32_e32 v163, v21, v130
	v_fmac_f32_e32 v164, v22, v130
	v_fmac_f32_e32 v165, v23, v130
	v_fmac_f32_e32 v158, v24, v131
	v_fmac_f32_e32 v159, v25, v131
	v_fmac_f32_e32 v160, v26, v131
	v_fmac_f32_e32 v161, v27, v131
	v_fmac_f32_e32 v162, v28, v131
	v_fmac_f32_e32 v163, v29, v131
	v_fmac_f32_e32 v164, v30, v131
	v_fmac_f32_e32 v165, v31, v131
	s_waitcnt lgkmcnt(1)
	v_pk_add_f32 v[138:139], v[138:139], 1.0 op_sel_hi:[1,0]
	v_pk_add_f32 v[140:141], v[140:141], 1.0 op_sel_hi:[1,0]
	s_waitcnt lgkmcnt(0)
	v_pk_fma_f32 v[148:149], v[148:149], v[138:139], v[142:143]
	v_pk_fma_f32 v[150:151], v[150:151], v[140:141], v[144:145]
	v_cvt_pk_bf16_f32 v138, v148, v149
	v_cvt_pk_bf16_f32 v139, v150, v151
	global_store_dwordx2 v[128:129], v[138:139], off offset:512
	ds_read_b128 v[138:141], v237 offset:7168
	s_nop 0
	ds_read_b128 v[142:145], v237 offset:3072
	v_fmac_f32_e32 v158, v32, v148
	v_fmac_f32_e32 v159, v33, v148
	v_fmac_f32_e32 v160, v34, v148
	v_fmac_f32_e32 v161, v35, v148
	v_fmac_f32_e32 v162, v36, v148
	v_fmac_f32_e32 v163, v37, v148
	v_fmac_f32_e32 v164, v38, v148
	v_fmac_f32_e32 v165, v39, v148
	v_fmac_f32_e32 v158, v40, v149
	v_fmac_f32_e32 v159, v41, v149
	v_fmac_f32_e32 v160, v42, v149
	v_fmac_f32_e32 v161, v43, v149
	v_fmac_f32_e32 v162, v44, v149
	v_fmac_f32_e32 v163, v45, v149
	v_fmac_f32_e32 v164, v46, v149
	v_fmac_f32_e32 v165, v47, v149
	v_fmac_f32_e32 v158, v48, v150
	v_fmac_f32_e32 v159, v49, v150
	v_fmac_f32_e32 v160, v50, v150
	v_fmac_f32_e32 v161, v51, v150
	v_fmac_f32_e32 v162, v52, v150
	v_fmac_f32_e32 v163, v53, v150
	v_fmac_f32_e32 v164, v54, v150
	v_fmac_f32_e32 v165, v55, v150
	v_fmac_f32_e32 v158, v56, v151
	v_fmac_f32_e32 v159, v57, v151
	v_fmac_f32_e32 v160, v58, v151
	v_fmac_f32_e32 v161, v59, v151
	v_fmac_f32_e32 v162, v60, v151
	v_fmac_f32_e32 v163, v61, v151
	v_fmac_f32_e32 v164, v62, v151
	v_fmac_f32_e32 v165, v63, v151
	s_waitcnt lgkmcnt(1)
	v_pk_add_f32 v[132:133], v[138:139], 1.0 op_sel_hi:[1,0]
	v_pk_add_f32 v[134:135], v[140:141], 1.0 op_sel_hi:[1,0]
	s_waitcnt lgkmcnt(0)
	v_pk_fma_f32 v[140:141], v[152:153], v[132:133], v[142:143]
	v_pk_fma_f32 v[142:143], v[154:155], v[134:135], v[144:145]
	v_cvt_pk_bf16_f32 v132, v140, v141
	v_cvt_pk_bf16_f32 v133, v142, v143
	global_store_dwordx2 v[128:129], v[132:133], off offset:1024
	ds_read_b128 v[132:135], v237 offset:4096
	s_nop 0
	ds_read_b128 v[136:139], v237 offset:8192
	v_fmac_f32_e32 v158, v64, v140
	v_fmac_f32_e32 v159, v65, v140
	v_fmac_f32_e32 v160, v66, v140
	v_fmac_f32_e32 v161, v67, v140
	v_fmac_f32_e32 v162, v68, v140
	v_fmac_f32_e32 v163, v69, v140
	v_fmac_f32_e32 v164, v70, v140
	v_fmac_f32_e32 v165, v71, v140
	v_fmac_f32_e32 v158, v72, v141
	v_fmac_f32_e32 v159, v73, v141
	v_fmac_f32_e32 v160, v74, v141
	v_fmac_f32_e32 v161, v75, v141
	v_fmac_f32_e32 v162, v76, v141
	v_fmac_f32_e32 v163, v77, v141
	v_fmac_f32_e32 v164, v78, v141
	v_fmac_f32_e32 v165, v79, v141
	v_fmac_f32_e32 v158, v80, v142
	v_fmac_f32_e32 v159, v81, v142
	v_fmac_f32_e32 v160, v82, v142
	v_fmac_f32_e32 v161, v83, v142
	v_fmac_f32_e32 v162, v84, v142
	v_fmac_f32_e32 v163, v85, v142
	v_fmac_f32_e32 v164, v86, v142
	v_fmac_f32_e32 v165, v87, v142
	v_fmac_f32_e32 v158, v88, v143
	v_fmac_f32_e32 v159, v89, v143
	v_fmac_f32_e32 v160, v90, v143
	v_fmac_f32_e32 v161, v91, v143
	v_fmac_f32_e32 v162, v92, v143
	v_fmac_f32_e32 v163, v93, v143
	v_fmac_f32_e32 v164, v94, v143
	v_fmac_f32_e32 v165, v95, v143
	s_waitcnt lgkmcnt(0)
; DI void phase1(const Params& p, unsigned char* smem) {
;     ...
; #pragma unroll
;                 for (int e = 0; e < 4; ++e) {
;                     const float4 w0 = gw0[i * 4 + e], w1 = gw1[i * 4 + e];
;                     ga[0] += o[e] * w0.x; ga[1] += o[e] * w0.y; ga[2] += o[e] * w0.z; ga[3] += o[e] * w0.w;
;                     ga[4] += o[e] * w1.x; ga[5] += o[e] * w1.y; ga[6] += o[e] * w1.z; ga[7] += o[e] * w1.w;
;                 }
;             }
; #pragma unroll
;             for (int j = 0; j < 8; ++j) ga[j] = wsum(ga[j]);
	v_pk_add_f32 v[130:131], v[136:137], 1.0 op_sel_hi:[1,0]
	s_nop 0
	v_pk_fma_f32 v[130:131], v[156:157], v[130:131], v[132:133]
	v_pk_add_f32 v[136:137], v[138:139], 1.0 op_sel_hi:[1,0]
	v_fmac_f32_e32 v158, v96, v130
	v_fmac_f32_e32 v159, v97, v130
	v_fmac_f32_e32 v160, v98, v130
	v_fmac_f32_e32 v161, v99, v130
	v_fmac_f32_e32 v162, v100, v130
	v_fmac_f32_e32 v163, v101, v130
	v_fmac_f32_e32 v164, v102, v130
	v_fmac_f32_e32 v165, v103, v130
	v_pk_fma_f32 v[132:133], v[146:147], v[136:137], v[134:135]
	v_fmac_f32_e32 v158, v104, v131
	v_fmac_f32_e32 v159, v105, v131
	v_fmac_f32_e32 v160, v106, v131
	v_fmac_f32_e32 v161, v107, v131
	v_fmac_f32_e32 v162, v108, v131
	v_fmac_f32_e32 v163, v109, v131
	v_fmac_f32_e32 v164, v110, v131
	v_fmac_f32_e32 v165, v111, v131
	v_fmac_f32_e32 v158, v112, v132
	v_fmac_f32_e32 v159, v113, v132
	v_fmac_f32_e32 v160, v114, v132
	v_fmac_f32_e32 v161, v115, v132
	v_fmac_f32_e32 v162, v116, v132
	v_fmac_f32_e32 v163, v117, v132
	v_fmac_f32_e32 v164, v118, v132
	v_fmac_f32_e32 v165, v119, v132
	v_cvt_pk_bf16_f32 v134, v130, v131
	v_cvt_pk_bf16_f32 v135, v132, v133
	v_fmac_f32_e32 v158, v120, v133
	v_fmac_f32_e32 v159, v121, v133
	v_fmac_f32_e32 v160, v122, v133
	v_fmac_f32_e32 v161, v123, v133
	v_fmac_f32_e32 v162, v124, v133
	v_fmac_f32_e32 v163, v125, v133
	v_fmac_f32_e32 v164, v126, v133
	v_fmac_f32_e32 v165, v127, v133
	global_store_dwordx2 v[128:129], v[134:135], off offset:1536
	v_add_f32_dpp v128, v158, v158 quad_perm:[1,0,3,2] row_mask:0xf bank_mask:0xf bound_ctrl:1
	v_add_f32_dpp v129, v159, v159 quad_perm:[1,0,3,2] row_mask:0xf bank_mask:0xf bound_ctrl:1
	v_add_f32_dpp v130, v160, v160 quad_perm:[1,0,3,2] row_mask:0xf bank_mask:0xf bound_ctrl:1
	v_add_f32_dpp v131, v161, v161 quad_perm:[1,0,3,2] row_mask:0xf bank_mask:0xf bound_ctrl:1
	v_add_f32_dpp v132, v162, v162 quad_perm:[1,0,3,2] row_mask:0xf bank_mask:0xf bound_ctrl:1
	v_add_f32_dpp v133, v163, v163 quad_perm:[1,0,3,2] row_mask:0xf bank_mask:0xf bound_ctrl:1
	v_add_f32_dpp v134, v164, v164 quad_perm:[1,0,3,2] row_mask:0xf bank_mask:0xf bound_ctrl:1
	v_add_f32_dpp v135, v165, v165 quad_perm:[1,0,3,2] row_mask:0xf bank_mask:0xf bound_ctrl:1
	v_add_f32_dpp v128, v128, v128 quad_perm:[2,3,0,1] row_mask:0xf bank_mask:0xf bound_ctrl:1
	v_add_f32_dpp v129, v129, v129 quad_perm:[2,3,0,1] row_mask:0xf bank_mask:0xf bound_ctrl:1
	v_add_f32_dpp v130, v130, v130 quad_perm:[2,3,0,1] row_mask:0xf bank_mask:0xf bound_ctrl:1
	v_add_f32_dpp v131, v131, v131 quad_perm:[2,3,0,1] row_mask:0xf bank_mask:0xf bound_ctrl:1
	v_add_f32_dpp v132, v132, v132 quad_perm:[2,3,0,1] row_mask:0xf bank_mask:0xf bound_ctrl:1
	v_add_f32_dpp v133, v133, v133 quad_perm:[2,3,0,1] row_mask:0xf bank_mask:0xf bound_ctrl:1
	v_add_f32_dpp v134, v134, v134 quad_perm:[2,3,0,1] row_mask:0xf bank_mask:0xf bound_ctrl:1
	v_add_f32_dpp v135, v135, v135 quad_perm:[2,3,0,1] row_mask:0xf bank_mask:0xf bound_ctrl:1
	v_add_f32_dpp v128, v128, v128 row_half_mirror row_mask:0xf bank_mask:0xf bound_ctrl:1
	v_add_f32_dpp v129, v129, v129 row_half_mirror row_mask:0xf bank_mask:0xf bound_ctrl:1
	v_add_f32_dpp v130, v130, v130 row_half_mirror row_mask:0xf bank_mask:0xf bound_ctrl:1
	v_add_f32_dpp v131, v131, v131 row_half_mirror row_mask:0xf bank_mask:0xf bound_ctrl:1
	v_add_f32_dpp v132, v132, v132 row_half_mirror row_mask:0xf bank_mask:0xf bound_ctrl:1
	v_add_f32_dpp v133, v133, v133 row_half_mirror row_mask:0xf bank_mask:0xf bound_ctrl:1
	v_add_f32_dpp v134, v134, v134 row_half_mirror row_mask:0xf bank_mask:0xf bound_ctrl:1
	v_add_f32_dpp v135, v135, v135 row_half_mirror row_mask:0xf bank_mask:0xf bound_ctrl:1
	v_add_f32_dpp v128, v128, v128 row_mirror row_mask:0xf bank_mask:0xf bound_ctrl:1
	v_add_f32_dpp v129, v129, v129 row_mirror row_mask:0xf bank_mask:0xf bound_ctrl:1
	v_add_f32_dpp v130, v130, v130 row_mirror row_mask:0xf bank_mask:0xf bound_ctrl:1
	v_add_f32_dpp v131, v131, v131 row_mirror row_mask:0xf bank_mask:0xf bound_ctrl:1
	v_add_f32_dpp v132, v132, v132 row_mirror row_mask:0xf bank_mask:0xf bound_ctrl:1
	v_add_f32_dpp v133, v133, v133 row_mirror row_mask:0xf bank_mask:0xf bound_ctrl:1
	v_add_f32_dpp v134, v134, v134 row_mirror row_mask:0xf bank_mask:0xf bound_ctrl:1
	v_add_f32_dpp v135, v135, v135 row_mirror row_mask:0xf bank_mask:0xf bound_ctrl:1
	v_readlane_b32 s16, v128, 0
	v_readlane_b32 s31, v128, 16
	v_readlane_b32 s17, v128, 32
	v_readlane_b32 s30, v128, 48
	v_readlane_b32 s34, v129, 0
	v_readlane_b32 s42, v129, 16
	v_readlane_b32 s35, v129, 32
	v_readlane_b32 s41, v129, 48
	v_readlane_b32 s43, v130, 0
	v_readlane_b32 s46, v130, 16
	v_readlane_b32 s44, v130, 32
	v_readlane_b32 s45, v130, 48
	v_readlane_b32 s47, v131, 0
	v_readlane_b32 s50, v131, 16
	v_readlane_b32 s48, v131, 32
	v_readlane_b32 s49, v131, 48
	v_readlane_b32 s51, v132, 0
	v_readlane_b32 s55, v132, 16
	v_readlane_b32 s52, v132, 32
	v_readlane_b32 s53, v132, 48
	v_readlane_b32 s56, v133, 0
	v_readlane_b32 s73, v133, 16
	v_readlane_b32 s57, v133, 32
	v_readlane_b32 s72, v133, 48
	v_readlane_b32 s74, v134, 0
	v_readlane_b32 s83, v134, 16
	v_readlane_b32 s75, v134, 32
	v_readlane_b32 s82, v134, 48
	v_readlane_b32 s84, v135, 0
	v_readlane_b32 s87, v135, 16
	v_readlane_b32 s85, v135, 32
	v_readlane_b32 s86, v135, 48
	s_and_saveexec_b64 s[28:29], vcc
	s_cbranch_execz .LBB0_188
; DI float logsig(float x) { return (x < 0.f) ? (x - log1pf(__expf(x))) : (-log1pf(__expf(-x))); }
; DI void phase1(const Params& p, unsigned char* smem) {
;     ...
;             if (lane < 8) {
;                 float val = ga[0];
; #pragma unroll
;                 for (int j = 1; j < 8; ++j) val = (lane == j) ? ga[j] : val;
;                 val += p.in[5][2048 + lane];
;                 const int b = row >> 13, sidx = row & 8191;
;                 if (lane < 4) ig[(size_t)(b * 4 + lane) * 8192 + sidx] = val;
;                 else lf[(size_t)(b * 4 + lane - 4) * 8192 + sidx] = logsig(val);
;             }
	v_mov_b32_e32 v134, s42
	v_mov_b32_e32 v135, s31
	v_mov_b32_e32 v133, s46
	v_add_f32_e32 v134, s34, v134
	v_add_f32_e32 v135, s16, v135
	v_mov_b32_e32 v132, s50
	v_add_f32_e32 v133, s43, v133
	v_add_f32_e32 v134, s35, v134
	v_add_f32_e32 v135, s17, v135
	v_mov_b32_e32 v131, s55
	v_add_f32_e32 v132, s47, v132
	v_add_f32_e32 v133, s44, v133
	v_add_f32_e32 v134, s41, v134
	v_add_f32_e32 v135, s30, v135
	v_mov_b32_e32 v130, s73
	v_add_f32_e32 v131, s51, v131
	v_add_f32_e32 v132, s48, v132
	v_add_f32_e32 v133, s45, v133
	v_cndmask_b32_e64 v134, v135, v134, s[0:1]
	v_mov_b32_e32 v129, s83
	v_add_f32_e32 v130, s56, v130
	v_add_f32_e32 v131, s52, v131
	v_add_f32_e32 v132, s49, v132
	v_cndmask_b32_e64 v133, v134, v133, s[14:15]
	v_mov_b32_e32 v128, s87
	v_add_f32_e32 v129, s74, v129
	v_add_f32_e32 v130, s57, v130
	v_add_f32_e32 v131, s53, v131
	v_cndmask_b32_e64 v132, v133, v132, s[4:5]
	v_add_f32_e32 v128, s84, v128
	v_add_f32_e32 v129, s75, v129
	v_add_f32_e32 v130, s72, v130
	v_cndmask_b32_e64 v131, v132, v131, s[6:7]
	v_add_f32_e32 v128, s85, v128
	v_add_f32_e32 v129, s82, v129
	v_cndmask_b32_e64 v130, v131, v130, s[8:9]
	v_add_f32_e32 v128, s86, v128
	v_cndmask_b32_e64 v129, v130, v129, s[10:11]
	v_cndmask_b32_e64 v128, v129, v128, s[12:13]
	ds_write_b32 v253, v128 offset:96
	s_or_b64 exec, exec, s[28:29]
	s_waitcnt lgkmcnt(0)
	s_and_saveexec_b64 s[28:29], s[96:97]
	ds_read_b32 v128, v253
	v_and_b32_e32 v129, 7, v230
	v_ashrrev_i32_e32 v130, 13, v176
	v_lshrrev_b32_e32 v194, 3, v230
	v_lshl_add_u32 v210, v130, 2, v129
	v_add_u32_e32 v194, v176, v194
	v_add_u32_e32 v200, -4, v210
	v_ashrrev_i32_e32 v211, 31, v210
	v_ashrrev_i32_e32 v201, 31, v200
	v_lshlrev_b64 v[210:211], 15, v[210:211]
	v_lshlrev_b64 v[200:201], 15, v[200:201]
	v_lshl_add_u64 v[210:211], s[88:89], 0, v[210:211]
	v_lshl_add_u64 v[200:201], s[20:21], 0, v[200:201]
	s_waitcnt lgkmcnt(0)
	v_add_f32_e32 v128, v128, v252
	s_and_saveexec_b64 s[30:31], s[98:99]
	s_cbranch_execz .LBB0_187
	v_cmp_ngt_f32_e64 s[16:17], 0, v128
	s_and_saveexec_b64 s[34:35], s[16:17]
	s_xor_b64 s[34:35], exec, s[34:35]
	s_cbranch_execz .LBB0_217
	v_mul_f32_e32 v128, 0xbfb8aa3b, v128
	v_exp_f32_e32 v142, v128
	s_nop 0
	v_add_f32_e32 v130, 1.0, v142
	v_frexp_mant_f32_e32 v132, v130
	v_cvt_f64_f32_e32 v[128:129], v130
	v_frexp_exp_i32_f64_e32 v128, v[128:129]
	v_cmp_gt_f32_e64 s[16:17], s37, v132
	v_add_f32_e32 v131, -1.0, v130
	v_sub_f32_e32 v133, v131, v130
	v_subbrev_co_u32_e64 v136, s[16:17], 0, v128, s[16:17]
	v_sub_u32_e32 v128, 0, v136
	v_sub_f32_e32 v131, v142, v131
	v_add_f32_e32 v133, 1.0, v133
	v_ldexp_f32 v129, v130, v128
	v_add_f32_e32 v131, v131, v133
	v_add_f32_e32 v130, -1.0, v129
	v_add_f32_e32 v132, 1.0, v129
	v_ldexp_f32 v128, v131, v128
	v_add_f32_e32 v131, 1.0, v130
	v_add_f32_e32 v133, -1.0, v132
	v_sub_f32_e32 v131, v129, v131
	v_sub_f32_e32 v129, v129, v133
	v_add_f32_e32 v131, v128, v131
	v_add_f32_e32 v128, v128, v129
	v_add_f32_e32 v137, v132, v128
	v_rcp_f32_e32 v139, v137
	v_sub_f32_e32 v129, v137, v132
	v_sub_f32_e32 v138, v128, v129
	v_add_f32_e32 v129, v130, v131
	v_mul_f32_e32 v141, v129, v139
	v_sub_f32_e32 v128, v129, v130
	v_mul_f32_e32 v130, v137, v141
	v_fma_f32 v132, v141, v137, -v130
	v_fmac_f32_e32 v132, v141, v138
	v_sub_f32_e32 v140, v131, v128
	v_add_f32_e32 v128, v130, v132
	v_sub_f32_e32 v131, v129, v128
	v_pk_add_f32 v[134:135], v[128:129], v[130:131] neg_lo:[0,1] neg_hi:[0,1]
	v_mov_b32_e32 v133, v128
	v_pk_add_f32 v[128:129], v[134:135], v[132:133] neg_lo:[0,1] neg_hi:[0,1]
	v_cmp_neq_f32_e64 s[16:17], s39, v142
	v_add_f32_e32 v129, v140, v129
	v_add_f32_e32 v128, v128, v129
	v_add_f32_e32 v129, v131, v128
	v_mul_f32_e32 v140, v139, v129
	v_mul_f32_e32 v130, v137, v140
	v_fma_f32 v132, v140, v137, -v130
	v_fmac_f32_e32 v132, v140, v138
	v_sub_f32_e32 v131, v131, v129
	v_add_f32_e32 v137, v128, v131
	v_add_f32_e32 v128, v130, v132
	v_sub_f32_e32 v131, v129, v128
	v_pk_add_f32 v[134:135], v[128:129], v[130:131] neg_lo:[0,1] neg_hi:[0,1]
	v_mov_b32_e32 v133, v128
	v_pk_add_f32 v[128:129], v[134:135], v[132:133] neg_lo:[0,1] neg_hi:[0,1]
	s_nop 0
	v_add_f32_e32 v129, v137, v129
	v_add_f32_e32 v128, v128, v129
	v_add_f32_e32 v129, v141, v140
	v_add_f32_e32 v128, v131, v128
	v_sub_f32_e32 v130, v129, v141
	v_mul_f32_e32 v128, v139, v128
	v_sub_f32_e32 v130, v140, v130
	v_add_f32_e32 v130, v130, v128
	v_add_f32_e32 v132, v129, v130
	v_mul_f32_e32 v133, v132, v132
	v_fmamk_f32 v128, v133, 0x3e9b6dac, v233
	v_fmaak_f32 v193, v133, v128, 0x3f2aaada
	v_cvt_f32_i32_e32 v128, v136
	v_sub_f32_e32 v129, v132, v129
	v_sub_f32_e32 v129, v130, v129
	v_ldexp_f32 v134, v129, 1
	v_mul_f32_e32 v129, v132, v133
	v_ldexp_f32 v131, v132, 1
	v_pk_mul_f32 v[132:133], v[128:129], v[192:193]
	s_nop 0
	v_fma_f32 v130, v128, s38, -v132
	v_fmac_f32_e32 v130, 0xb102e308, v128
	v_pk_add_f32 v[128:129], v[132:133], v[130:131]
	s_nop 0
	v_sub_f32_e32 v131, v129, v131
	v_sub_f32_e32 v131, v133, v131
	v_add_f32_e32 v135, v134, v131
	v_mov_b32_e32 v134, v132
	v_pk_add_f32 v[132:133], v[128:129], v[132:133] neg_lo:[0,1] neg_hi:[0,1]
	v_pk_add_f32 v[136:137], v[128:129], v[134:135]
	v_mov_b32_e32 v131, v128
	v_mov_b32_e32 v133, v137
	v_pk_add_f32 v[138:139], v[130:131], v[132:133] neg_lo:[0,1] neg_hi:[0,1]
	v_pk_add_f32 v[130:131], v[130:131], v[132:133]
	v_mov_b32_e32 v134, v135
	v_pk_add_f32 v[132:133], v[130:131], v[128:129] op_sel:[1,0] op_sel_hi:[0,1] neg_lo:[0,1] neg_hi:[0,1]
	v_pk_add_f32 v[140:141], v[136:137], v[132:133] op_sel_hi:[1,0] neg_lo:[0,1] neg_hi:[0,1]
	v_mov_b32_e32 v136, v137
	v_mov_b32_e32 v137, v131
	v_pk_mov_b32 v[132:133], v[128:129], v[132:133] op_sel:[1,0]
	v_mov_b32_e32 v135, v128
	v_pk_add_f32 v[132:133], v[136:137], v[132:133] neg_lo:[0,1] neg_hi:[0,1]
	v_mov_b32_e32 v140, v138
	v_pk_add_f32 v[128:129], v[134:135], v[132:133] neg_lo:[0,1] neg_hi:[0,1]
	v_mov_b32_e32 v139, v131
	v_pk_add_f32 v[132:133], v[140:141], v[128:129]
	s_nop 0
	v_pk_add_f32 v[134:135], v[132:133], v[132:133] op_sel:[0,1] op_sel_hi:[1,0]
	s_nop 0
	v_pk_add_f32 v[130:131], v[130:131], v[134:135] op_sel:[1,0] op_sel_hi:[0,1]
	v_mov_b32_e32 v133, v130
	v_pk_add_f32 v[136:137], v[132:133], v[138:139] neg_lo:[0,1] neg_hi:[0,1]
	v_mov_b32_e32 v129, v134
	v_sub_f32_e32 v131, v132, v136
	v_pk_add_f32 v[128:129], v[128:129], v[136:137] neg_lo:[0,1] neg_hi:[0,1]
	v_sub_f32_e32 v131, v138, v131
	v_add_f32_e32 v128, v128, v131
	v_add_f32_e32 v128, v128, v129
	v_add_f32_e32 v128, v130, v128
	v_cndmask_b32_e64 v128, v234, v128, s[16:17]
	v_cmp_ngt_f32_e64 s[16:17], -1.0, v142
	s_nop 1
	v_cndmask_b32_e64 v128, v235, v128, s[16:17]
	v_cmp_neq_f32_e64 s[16:17], -1.0, v142
	s_nop 1
	v_cndmask_b32_e64 v128, v236, v128, s[16:17]
	v_cmp_lt_f32_e64 s[16:17], |v142|, s40
	s_nop 1
	v_cndmask_b32_e64 v128, v128, v142, s[16:17]
	v_xor_b32_e32 v128, 0x80000000, v128
